# adds a peeled first K-iteration per unit in all four GEMM loops whose first two vmcnt waits are relaxed by the epilogue store count (stores drain while the next unit starts)
# speedup vs baseline: 1.0122x; 1.0015x over previous
; #define PG8_STAGE(bufoff, gbase, voff) do { _Pragma("unroll") for (int _i = 0; _i < 2; ++_i) \
;         __builtin_amdgcn_global_load_lds((const unsigned*)((const char*)(gbase) + (voff)[_i]), (LAS unsigned*)(lds + (bufoff) + ldsw + _i * 8192), 16, 0, 0); } while (0)
; #define PG8_LDA(dst, b, h) do { _Pragma("unroll") for (int m = 0; m < 4; ++m) _Pragma("unroll") for (int k = 0; k < 2; ++k) dst[m][k] = *(const LAS bf16x8*)(lds + PG8_SA(b, h) + aoff + m * 2048 + k * 1024); } while (0)
; #define PG8_LDB(dst, b, h) do { _Pragma("unroll") for (int n = 0; n < 2; ++n) _Pragma("unroll") for (int k = 0; k < 2; ++k) dst[n][k] = *(const LAS bf16x8*)(lds + PG8_SB(b, h) + boff + n * 2048 + k * 1024); } while (0)
; #define PG8_MMA(ai, bj, At, Bt) do { __builtin_amdgcn_s_setprio(1); _Pragma("unroll") for (int m = 0; m < 4; ++m) _Pragma("unroll") for (int n = 0; n < 2; ++n) _Pragma("unroll") for (int k = 0; k < 2; ++k) \
;         acc[ai][bj][m][n] = __builtin_amdgcn_mfma_f32_16x16x32_bf16(Bt[n][k], At[m][k], acc[ai][bj][m][n], 0, 0, 0); __builtin_amdgcn_s_setprio(0); } while (0)
; #define PG8_WAIT_V(n) asm volatile("s_waitcnt vmcnt(" #n ")" ::: "memory")
; template <class Epi, class Sched, int KC, bool ALIGN_EPI = false, bool SP2 = false, bool ATILED = false>
; __device__ __forceinline__ void gemm_phase(LAS unsigned char* lds, const Gemm g, const Sched& S, const Epi& E, int wave_s) {
;     ...
;         const bool has_next = S.next(ui + 1, nxt);
;         const char* nA = has_next ? (const char*)g.A + (size_t)nxt.pm * tstepA : cA; const char* nB = has_next ? (const char*)g.Bt + (size_t)nxt.pn * tstep : cB;
;         for (int t = 0; t < nt; t += 2) {
;             const bool last = (t == nt - 2);
;             const char* a1 = cA + PG8_AOFF(t + 1);
;             const char* a2 = last ? nA : cA + PG8_AOFF(t + 2); const char* b2 = last ? nB : cB + (size_t)(t + 2) * kstep;
;             const char* a3 = a2 + kstep; const char* b3 = b2 + kstep;
;             if (last && has_next) S.a_ready(nxt);
;             if constexpr (SP2) {
;             PG8_LDB(B0, 0, 0); PG8_LDB(B1, 0, 1); PG8_SCHED; PG8_LDA(At, 0, 0); PG8_STAGE(PG8_SA(1, 1), a1 + hstepA, voffA);
;             PG8_WAIT_V(8); PG8_WAIT_L(0); PG8_BAR; PG8_MMA(0, 0, At, B0); PG8_MMA(0, 1, At, B1); PG8_BAR; PG8_SCHED;
;     ...
;                     for (int n = 0; n < 2; ++n) acc[a][b][m][n] = (f32x4){0.f, 0.f, 0.f, 0.f};
.LBB0_232:
	s_ashr_i32 s19, s18, 31
	s_lshl_b64 s[20:21], s[18:19], 17
	s_add_u32 s20, s39, s20
	s_addc_u32 s21, s40, s21
	s_and_b64 s[22:23], s[6:7], exec
	s_cselect_b32 s19, s21, s27
	s_cselect_b32 s53, s20, s26
	s_ashr_i32 s17, s16, 31
	s_lshl_b64 s[22:23], s[16:17], 20
	s_add_u32 s22, s41, s22
	s_addc_u32 s23, s42, s23
	s_and_b64 s[30:31], s[6:7], exec
	s_cselect_b32 s17, s23, s29
	s_cselect_b32 s54, s22, s28
	s_add_u32 s55, s28, 0x100
	v_mov_b32_e32 v2, 0
	s_addc_u32 s56, s29, 0
	s_mov_b32 s57, -2
	s_mov_b64 s[28:29], 0
	s_mov_b32 s58, 0x400000
	v_mov_b32_e32 v3, v2
	v_mov_b32_e32 v4, v2
	v_mov_b32_e32 v5, v2
	v_mov_b32_e32 v14, v2
	v_mov_b32_e32 v15, v2
	v_mov_b32_e32 v16, v2
	v_mov_b32_e32 v17, v2
	v_mov_b32_e32 v22, v2
	v_mov_b32_e32 v23, v2
	v_mov_b32_e32 v24, v2
	v_mov_b32_e32 v25, v2
	v_mov_b32_e32 v30, v2
	v_mov_b32_e32 v31, v2
	v_mov_b32_e32 v32, v2
	v_mov_b32_e32 v33, v2
	v_mov_b32_e32 v38, v2
	v_mov_b32_e32 v39, v2
	v_mov_b32_e32 v40, v2
	v_mov_b32_e32 v41, v2
	v_mov_b32_e32 v46, v2
	v_mov_b32_e32 v47, v2
	v_mov_b32_e32 v48, v2
	v_mov_b32_e32 v49, v2
	v_mov_b32_e32 v54, v2
	v_mov_b32_e32 v55, v2
	v_mov_b32_e32 v56, v2
	v_mov_b32_e32 v57, v2
	v_mov_b32_e32 v62, v2
	v_mov_b32_e32 v63, v2
	v_mov_b32_e32 v64, v2
	v_mov_b32_e32 v65, v2
	v_mov_b32_e32 v6, v2
	v_mov_b32_e32 v7, v2
	v_mov_b32_e32 v8, v2
	v_mov_b32_e32 v9, v2
	v_mov_b32_e32 v10, v2
	v_mov_b32_e32 v11, v2
	v_mov_b32_e32 v12, v2
	v_mov_b32_e32 v13, v2
	v_mov_b32_e32 v18, v2
	v_mov_b32_e32 v19, v2
	v_mov_b32_e32 v20, v2
	v_mov_b32_e32 v21, v2
	v_mov_b32_e32 v26, v2
	v_mov_b32_e32 v27, v2
	v_mov_b32_e32 v28, v2
	v_mov_b32_e32 v29, v2
	v_mov_b32_e32 v34, v2
	v_mov_b32_e32 v35, v2
	v_mov_b32_e32 v36, v2
	v_mov_b32_e32 v37, v2
	v_mov_b32_e32 v42, v2
	v_mov_b32_e32 v43, v2
	v_mov_b32_e32 v44, v2
	v_mov_b32_e32 v45, v2
	v_mov_b32_e32 v50, v2
	v_mov_b32_e32 v51, v2
	v_mov_b32_e32 v52, v2
	v_mov_b32_e32 v53, v2
	v_mov_b32_e32 v58, v2
	v_mov_b32_e32 v59, v2
	v_mov_b32_e32 v60, v2
	v_mov_b32_e32 v61, v2
	v_mov_b32_e32 v70, v2
	v_mov_b32_e32 v71, v2
	v_mov_b32_e32 v72, v2
	v_mov_b32_e32 v73, v2
	v_mov_b32_e32 v78, v2
	v_mov_b32_e32 v79, v2
	v_mov_b32_e32 v80, v2
	v_mov_b32_e32 v81, v2
	v_mov_b32_e32 v86, v2
	v_mov_b32_e32 v87, v2
	v_mov_b32_e32 v88, v2
	v_mov_b32_e32 v89, v2
	v_mov_b32_e32 v94, v2
	v_mov_b32_e32 v95, v2
	v_mov_b32_e32 v96, v2
	v_mov_b32_e32 v97, v2
	v_mov_b32_e32 v102, v2
	v_mov_b32_e32 v103, v2
	v_mov_b32_e32 v104, v2
	v_mov_b32_e32 v105, v2
	v_mov_b32_e32 v110, v2
	v_mov_b32_e32 v111, v2
	v_mov_b32_e32 v112, v2
	v_mov_b32_e32 v113, v2
	v_mov_b32_e32 v118, v2
	v_mov_b32_e32 v119, v2
	v_mov_b32_e32 v120, v2
	v_mov_b32_e32 v121, v2
	v_mov_b32_e32 v126, v2
	v_mov_b32_e32 v127, v2
	v_mov_b32_e32 v128, v2
	v_mov_b32_e32 v129, v2
	v_mov_b32_e32 v66, v2
	v_mov_b32_e32 v67, v2
	v_mov_b32_e32 v68, v2
	v_mov_b32_e32 v69, v2
	v_mov_b32_e32 v74, v2
	v_mov_b32_e32 v75, v2
	v_mov_b32_e32 v76, v2
	v_mov_b32_e32 v77, v2
	v_mov_b32_e32 v82, v2
	v_mov_b32_e32 v83, v2
	v_mov_b32_e32 v84, v2
	v_mov_b32_e32 v85, v2
	v_mov_b32_e32 v90, v2
	v_mov_b32_e32 v91, v2
	v_mov_b32_e32 v92, v2
	v_mov_b32_e32 v93, v2
	v_mov_b32_e32 v98, v2
	v_mov_b32_e32 v99, v2
	v_mov_b32_e32 v100, v2
	v_mov_b32_e32 v101, v2
	v_mov_b32_e32 v106, v2
	v_mov_b32_e32 v107, v2
	v_mov_b32_e32 v108, v2
	v_mov_b32_e32 v109, v2
	v_mov_b32_e32 v114, v2
	v_mov_b32_e32 v115, v2
	v_mov_b32_e32 v116, v2
	v_mov_b32_e32 v117, v2
	v_mov_b32_e32 v122, v2
	v_mov_b32_e32 v123, v2
	v_mov_b32_e32 v124, v2
	v_mov_b32_e32 v125, v2
	s_add_i32 s30, s58, 0xffc00000
	s_and_b32 s30, s30, 0x3800000
	s_and_b32 s31, s28, 0x100
	s_or_b32 s59, s31, s30
	s_and_b32 s34, s58, 0x7800000
	s_add_u32 s30, s28, 0x100
	s_addc_u32 s31, s29, 0
	s_and_b32 s35, s30, 0x100
	s_or_b32 s34, s34, s35
	s_add_u32 s34, s26, s34
	s_addc_u32 s35, s27, 0
	s_add_u32 s28, s55, s28
	s_addc_u32 s29, s56, s29
	s_add_i32 s62, 0, 0x10000
	s_cmp_eq_u32 s57, 28
	s_cselect_b32 s35, s19, s35
	s_cselect_b32 s34, s53, s34
	v_add_u32_e32 v139, s62, v163
	s_cselect_b32 s29, s17, s29
	s_cselect_b32 s28, s54, s28
	s_add_i32 s63, 0, 0x14000
	ds_read_b128 v[152:155], v139
	ds_read_b128 v[156:159], v139 offset:1024
	ds_read_b128 v[168:171], v139 offset:2048
	ds_read_b128 v[172:175], v139 offset:3072
	v_add_u32_e32 v139, s63, v163
	ds_read_b128 v[176:179], v139
	ds_read_b128 v[180:183], v139 offset:1024
	ds_read_b128 v[184:187], v139 offset:2048
	ds_read_b128 v[188:191], v139 offset:3072
	s_add_u32 s59, s26, s59
	s_addc_u32 s61, s27, 0
	s_add_u32 s60, s59, 0x10080
	s_addc_u32 s61, s61, 0
	s_add_i32 m0, s44, 0xc000
	ds_read_b128 v[198:201], v166
	ds_read_b128 v[202:205], v166 offset:1024
	ds_read_b128 v[206:209], v166 offset:2048
	ds_read_b128 v[210:213], v166 offset:3072
	ds_read_b128 v[214:217], v166 offset:4096
	ds_read_b128 v[218:221], v166 offset:5120
	ds_read_b128 v[222:225], v166 offset:6144
	ds_read_b128 v[226:229], v166 offset:7168
	global_load_lds_dwordx4 v136, s[60:61]
	s_add_i32 m0, s44, 0xe000
	s_nop 0
	global_load_lds_dwordx4 v132, s[60:61]
	s_waitcnt vmcnt(16)
	s_waitcnt lgkmcnt(0)
	s_barrier
; #define PG8_STAGE(bufoff, gbase, voff) do { _Pragma("unroll") for (int _i = 0; _i < 2; ++_i) \
;         __builtin_amdgcn_global_load_lds((const unsigned*)((const char*)(gbase) + (voff)[_i]), (LAS unsigned*)(lds + (bufoff) + ldsw + _i * 8192), 16, 0, 0); } while (0)
; #define PG8_LDA(dst, b, h) do { _Pragma("unroll") for (int m = 0; m < 4; ++m) _Pragma("unroll") for (int k = 0; k < 2; ++k) dst[m][k] = *(const LAS bf16x8*)(lds + PG8_SA(b, h) + aoff + m * 2048 + k * 1024); } while (0)
; #define PG8_MMA(ai, bj, At, Bt) do { __builtin_amdgcn_s_setprio(1); _Pragma("unroll") for (int m = 0; m < 4; ++m) _Pragma("unroll") for (int n = 0; n < 2; ++n) _Pragma("unroll") for (int k = 0; k < 2; ++k) \
;         acc[ai][bj][m][n] = __builtin_amdgcn_mfma_f32_16x16x32_bf16(Bt[n][k], At[m][k], acc[ai][bj][m][n], 0, 0, 0); __builtin_amdgcn_s_setprio(0); } while (0)
; #define PG8_WAIT_V(n) asm volatile("s_waitcnt vmcnt(" #n ")" ::: "memory")
; #define PG8_WAIT_L(n) asm volatile("s_waitcnt lgkmcnt(" #n ")" ::: "memory")
; #define PG8_BAR __builtin_amdgcn_s_barrier()
; #define PG8_SCHED __builtin_amdgcn_sched_barrier(0)
; template <class Epi, class Sched, int KC, bool ALIGN_EPI = false, bool SP2 = false, bool ATILED = false>
; __device__ __forceinline__ void gemm_phase(LAS unsigned char* lds, const Gemm g, const Sched& S, const Epi& E, int wave_s) {
;     ...
;             PG8_WAIT_V(8); PG8_WAIT_L(0); PG8_BAR; PG8_MMA(0, 0, At, B0); PG8_MMA(0, 1, At, B1); PG8_BAR; PG8_SCHED;
;             PG8_LDA(At, 0, 1); PG8_STAGE(PG8_SB(0, 0), b2, voffB); PG8_STAGE(PG8_SB(0, 1), b2 + hstepB, voffB); PG8_STAGE(PG8_SA(0, 0), a2, voffA);
;             PG8_WAIT_V(8); PG8_WAIT_L(0); PG8_BAR; PG8_MMA(1, 0, At, B0); PG8_MMA(1, 1, At, B1); PG8_BAR; PG8_SCHED;
	s_waitcnt lgkmcnt(0)
	v_mfma_f32_16x16x32_bf16 v[122:125], v[152:155], v[198:201], v[122:125]
	v_mfma_f32_16x16x32_bf16 v[114:117], v[168:171], v[198:201], v[114:117]
	v_mfma_f32_16x16x32_bf16 v[106:109], v[152:155], v[206:209], v[106:109]
	v_mfma_f32_16x16x32_bf16 v[98:101], v[168:171], v[206:209], v[98:101]
	v_mfma_f32_16x16x32_bf16 v[90:93], v[152:155], v[214:217], v[90:93]
	v_mfma_f32_16x16x32_bf16 v[82:85], v[168:171], v[214:217], v[82:85]
	v_mfma_f32_16x16x32_bf16 v[74:77], v[152:155], v[222:225], v[74:77]
	v_mfma_f32_16x16x32_bf16 v[66:69], v[168:171], v[222:225], v[66:69]
	v_mfma_f32_16x16x32_bf16 v[122:125], v[156:159], v[202:205], v[122:125]
	v_mfma_f32_16x16x32_bf16 v[114:117], v[172:175], v[202:205], v[114:117]
	v_mfma_f32_16x16x32_bf16 v[106:109], v[156:159], v[210:213], v[106:109]
	v_mfma_f32_16x16x32_bf16 v[98:101], v[172:175], v[210:213], v[98:101]
	v_mfma_f32_16x16x32_bf16 v[90:93], v[156:159], v[218:221], v[90:93]
	v_mfma_f32_16x16x32_bf16 v[82:85], v[172:175], v[218:221], v[82:85]
	v_mfma_f32_16x16x32_bf16 v[74:77], v[156:159], v[226:229], v[74:77]
	v_mfma_f32_16x16x32_bf16 v[66:69], v[172:175], v[226:229], v[66:69]
	v_mfma_f32_16x16x32_bf16 v[126:129], v[176:179], v[198:201], v[126:129]
	v_mfma_f32_16x16x32_bf16 v[118:121], v[184:187], v[198:201], v[118:121]
	v_mfma_f32_16x16x32_bf16 v[110:113], v[176:179], v[206:209], v[110:113]
	v_mfma_f32_16x16x32_bf16 v[102:105], v[184:187], v[206:209], v[102:105]
	v_mfma_f32_16x16x32_bf16 v[94:97], v[176:179], v[214:217], v[94:97]
	v_mfma_f32_16x16x32_bf16 v[86:89], v[184:187], v[214:217], v[86:89]
	v_mfma_f32_16x16x32_bf16 v[78:81], v[176:179], v[222:225], v[78:81]
	v_mfma_f32_16x16x32_bf16 v[70:73], v[184:187], v[222:225], v[70:73]
	v_mfma_f32_16x16x32_bf16 v[126:129], v[180:183], v[202:205], v[126:129]
	v_mfma_f32_16x16x32_bf16 v[118:121], v[188:191], v[202:205], v[118:121]
	v_mfma_f32_16x16x32_bf16 v[110:113], v[180:183], v[210:213], v[110:113]
	v_mfma_f32_16x16x32_bf16 v[102:105], v[188:191], v[210:213], v[102:105]
	v_mfma_f32_16x16x32_bf16 v[94:97], v[180:183], v[218:221], v[94:97]
	v_mfma_f32_16x16x32_bf16 v[86:89], v[188:191], v[218:221], v[86:89]
	v_mfma_f32_16x16x32_bf16 v[78:81], v[180:183], v[226:229], v[78:81]
	v_mfma_f32_16x16x32_bf16 v[70:73], v[188:191], v[226:229], v[70:73]
	s_barrier
	s_add_u32 s100, s34, 0x80
	s_addc_u32 s101, s35, 0
	s_add_i32 s59, s62, s38
	s_mov_b32 m0, s59
	ds_read_b128 v[198:201], v166 offset:16384
	ds_read_b128 v[202:205], v166 offset:17408
	ds_read_b128 v[206:209], v166 offset:18432
	ds_read_b128 v[210:213], v166 offset:19456
	ds_read_b128 v[214:217], v166 offset:20480
	ds_read_b128 v[218:221], v166 offset:21504
	ds_read_b128 v[222:225], v166 offset:22528
	ds_read_b128 v[226:229], v166 offset:23552
	global_load_lds_dwordx4 v134, s[28:29]
	s_add_i32 m0, s59, 0x2000
	s_add_u32 s60, s28, 0x80000
	s_addc_u32 s61, s29, 0
	s_add_i32 s59, s63, s38
	global_load_lds_dwordx4 v130, s[28:29]
	s_mov_b32 m0, s59
	s_nop 0
	global_load_lds_dwordx4 v134, s[60:61]
	s_add_i32 m0, s59, 0x2000
	s_nop 0
	global_load_lds_dwordx4 v130, s[60:61]
	s_mov_b32 m0, s44
	s_nop 0
	global_load_lds_dwordx4 v136, s[34:35]
	s_mov_b32 m0, s45
	s_nop 0
	global_load_lds_dwordx4 v132, s[34:35]
	s_waitcnt vmcnt(16)
	s_waitcnt lgkmcnt(0)
	s_barrier
	s_waitcnt lgkmcnt(0)
	v_mfma_f32_16x16x32_bf16 v[58:61], v[152:155], v[198:201], v[58:61]
	v_mfma_f32_16x16x32_bf16 v[50:53], v[168:171], v[198:201], v[50:53]
	v_mfma_f32_16x16x32_bf16 v[42:45], v[152:155], v[206:209], v[42:45]
	v_mfma_f32_16x16x32_bf16 v[34:37], v[168:171], v[206:209], v[34:37]
	v_mfma_f32_16x16x32_bf16 v[26:29], v[152:155], v[214:217], v[26:29]
	v_mfma_f32_16x16x32_bf16 v[18:21], v[168:171], v[214:217], v[18:21]
	v_mfma_f32_16x16x32_bf16 v[10:13], v[152:155], v[222:225], v[10:13]
	v_mfma_f32_16x16x32_bf16 v[6:9], v[168:171], v[222:225], v[6:9]
	v_mfma_f32_16x16x32_bf16 v[58:61], v[156:159], v[202:205], v[58:61]
	v_mfma_f32_16x16x32_bf16 v[50:53], v[172:175], v[202:205], v[50:53]
	v_mfma_f32_16x16x32_bf16 v[42:45], v[156:159], v[210:213], v[42:45]
	v_mfma_f32_16x16x32_bf16 v[34:37], v[172:175], v[210:213], v[34:37]
	v_mfma_f32_16x16x32_bf16 v[26:29], v[156:159], v[218:221], v[26:29]
	v_mfma_f32_16x16x32_bf16 v[18:21], v[172:175], v[218:221], v[18:21]
	v_mfma_f32_16x16x32_bf16 v[10:13], v[156:159], v[226:229], v[10:13]
	v_mfma_f32_16x16x32_bf16 v[6:9], v[172:175], v[226:229], v[6:9]
	v_mfma_f32_16x16x32_bf16 v[62:65], v[176:179], v[198:201], v[62:65]
	v_mfma_f32_16x16x32_bf16 v[54:57], v[184:187], v[198:201], v[54:57]
	v_mfma_f32_16x16x32_bf16 v[46:49], v[176:179], v[206:209], v[46:49]
	v_mfma_f32_16x16x32_bf16 v[38:41], v[184:187], v[206:209], v[38:41]
	v_mfma_f32_16x16x32_bf16 v[30:33], v[176:179], v[214:217], v[30:33]
	v_mfma_f32_16x16x32_bf16 v[22:25], v[184:187], v[214:217], v[22:25]
	v_mfma_f32_16x16x32_bf16 v[14:17], v[176:179], v[222:225], v[14:17]
	v_mfma_f32_16x16x32_bf16 v[2:5], v[184:187], v[222:225], v[2:5]
	v_mfma_f32_16x16x32_bf16 v[62:65], v[180:183], v[202:205], v[62:65]
	v_mfma_f32_16x16x32_bf16 v[54:57], v[188:191], v[202:205], v[54:57]
	v_mfma_f32_16x16x32_bf16 v[46:49], v[180:183], v[210:213], v[46:49]
	v_mfma_f32_16x16x32_bf16 v[38:41], v[188:191], v[210:213], v[38:41]
	v_mfma_f32_16x16x32_bf16 v[30:33], v[180:183], v[218:221], v[30:33]
	v_mfma_f32_16x16x32_bf16 v[22:25], v[188:191], v[218:221], v[22:25]
	v_mfma_f32_16x16x32_bf16 v[14:17], v[180:183], v[226:229], v[14:17]
	v_mfma_f32_16x16x32_bf16 v[2:5], v[188:191], v[226:229], v[2:5]
	s_barrier
; #define PG8_STAGE(bufoff, gbase, voff) do { _Pragma("unroll") for (int _i = 0; _i < 2; ++_i) \
;         __builtin_amdgcn_global_load_lds((const unsigned*)((const char*)(gbase) + (voff)[_i]), (LAS unsigned*)(lds + (bufoff) + ldsw + _i * 8192), 16, 0, 0); } while (0)
; #define PG8_LDA(dst, b, h) do { _Pragma("unroll") for (int m = 0; m < 4; ++m) _Pragma("unroll") for (int k = 0; k < 2; ++k) dst[m][k] = *(const LAS bf16x8*)(lds + PG8_SA(b, h) + aoff + m * 2048 + k * 1024); } while (0)
; #define PG8_LDB(dst, b, h) do { _Pragma("unroll") for (int n = 0; n < 2; ++n) _Pragma("unroll") for (int k = 0; k < 2; ++k) dst[n][k] = *(const LAS bf16x8*)(lds + PG8_SB(b, h) + boff + n * 2048 + k * 1024); } while (0)
; #define PG8_MMA(ai, bj, At, Bt) do { __builtin_amdgcn_s_setprio(1); _Pragma("unroll") for (int m = 0; m < 4; ++m) _Pragma("unroll") for (int n = 0; n < 2; ++n) _Pragma("unroll") for (int k = 0; k < 2; ++k) \
;         acc[ai][bj][m][n] = __builtin_amdgcn_mfma_f32_16x16x32_bf16(Bt[n][k], At[m][k], acc[ai][bj][m][n], 0, 0, 0); __builtin_amdgcn_s_setprio(0); } while (0)
; #define PG8_WAIT_V(n) asm volatile("s_waitcnt vmcnt(" #n ")" ::: "memory")
; #define PG8_WAIT_L(n) asm volatile("s_waitcnt lgkmcnt(" #n ")" ::: "memory")
; #define PG8_BAR __builtin_amdgcn_s_barrier()
; #define PG8_SCHED __builtin_amdgcn_sched_barrier(0)
; template <class Epi, class Sched, int KC, bool ALIGN_EPI = false, bool SP2 = false, bool ATILED = false>
; __device__ __forceinline__ void gemm_phase(LAS unsigned char* lds, const Gemm g, const Sched& S, const Epi& E, int wave_s) {
;     ...
;             PG8_LDB(B0, 1, 0); PG8_LDB(B1, 1, 1); PG8_SCHED; PG8_LDA(At, 1, 0); PG8_STAGE(PG8_SA(0, 1), a2 + hstepA, voffA);
;             PG8_WAIT_V(8); PG8_WAIT_L(0); PG8_BAR; PG8_MMA(0, 0, At, B0); PG8_MMA(0, 1, At, B1); PG8_BAR; PG8_SCHED;
;             PG8_LDA(At, 1, 1); PG8_STAGE(PG8_SB(1, 0), b3, voffB); PG8_STAGE(PG8_SB(1, 1), b3 + hstepB, voffB); PG8_STAGE(PG8_SA(1, 0), a3, voffA);
;             PG8_WAIT_V(8); PG8_WAIT_L(0); PG8_BAR; PG8_MMA(1, 0, At, B0); PG8_MMA(1, 1, At, B1); PG8_BAR; PG8_SCHED;
	s_add_i32 s59, 0, 0x18000
	v_add_u32_e32 v139, s59, v163
	s_add_i32 s60, 0, 0x1c000
	ds_read_b128 v[152:155], v139
	ds_read_b128 v[156:159], v139 offset:1024
	ds_read_b128 v[168:171], v139 offset:2048
	ds_read_b128 v[172:175], v139 offset:3072
	v_add_u32_e32 v139, s60, v163
	ds_read_b128 v[176:179], v139
	ds_read_b128 v[180:183], v139 offset:1024
	ds_read_b128 v[184:187], v139 offset:2048
	ds_read_b128 v[188:191], v139 offset:3072
	s_add_u32 s34, s34, 0x10000
	s_addc_u32 s35, s35, 0
	s_mov_b32 m0, s46
	ds_read_b128 v[198:201], v166 offset:32768
	ds_read_b128 v[202:205], v166 offset:33792
	ds_read_b128 v[206:209], v166 offset:34816
	ds_read_b128 v[210:213], v166 offset:35840
	ds_read_b128 v[214:217], v166 offset:36864
	ds_read_b128 v[218:221], v166 offset:37888
	ds_read_b128 v[222:225], v166 offset:38912
	ds_read_b128 v[226:229], v166 offset:39936
	global_load_lds_dwordx4 v136, s[34:35]
	s_mov_b32 m0, s47
	s_nop 0
	global_load_lds_dwordx4 v132, s[34:35]
	s_waitcnt vmcnt(8)
	s_waitcnt lgkmcnt(0)
	s_barrier
	s_waitcnt lgkmcnt(0)
	v_mfma_f32_16x16x32_bf16 v[122:125], v[152:155], v[198:201], v[122:125]
	v_mfma_f32_16x16x32_bf16 v[114:117], v[168:171], v[198:201], v[114:117]
	v_mfma_f32_16x16x32_bf16 v[106:109], v[152:155], v[206:209], v[106:109]
	v_mfma_f32_16x16x32_bf16 v[98:101], v[168:171], v[206:209], v[98:101]
	v_mfma_f32_16x16x32_bf16 v[90:93], v[152:155], v[214:217], v[90:93]
	v_mfma_f32_16x16x32_bf16 v[82:85], v[168:171], v[214:217], v[82:85]
	v_mfma_f32_16x16x32_bf16 v[74:77], v[152:155], v[222:225], v[74:77]
	v_mfma_f32_16x16x32_bf16 v[66:69], v[168:171], v[222:225], v[66:69]
	v_mfma_f32_16x16x32_bf16 v[122:125], v[156:159], v[202:205], v[122:125]
	v_mfma_f32_16x16x32_bf16 v[114:117], v[172:175], v[202:205], v[114:117]
	v_mfma_f32_16x16x32_bf16 v[106:109], v[156:159], v[210:213], v[106:109]
	v_mfma_f32_16x16x32_bf16 v[98:101], v[172:175], v[210:213], v[98:101]
	v_mfma_f32_16x16x32_bf16 v[90:93], v[156:159], v[218:221], v[90:93]
	v_mfma_f32_16x16x32_bf16 v[82:85], v[172:175], v[218:221], v[82:85]
	v_mfma_f32_16x16x32_bf16 v[74:77], v[156:159], v[226:229], v[74:77]
	v_mfma_f32_16x16x32_bf16 v[66:69], v[172:175], v[226:229], v[66:69]
	v_mfma_f32_16x16x32_bf16 v[126:129], v[176:179], v[198:201], v[126:129]
	v_mfma_f32_16x16x32_bf16 v[118:121], v[184:187], v[198:201], v[118:121]
	v_mfma_f32_16x16x32_bf16 v[110:113], v[176:179], v[206:209], v[110:113]
	v_mfma_f32_16x16x32_bf16 v[102:105], v[184:187], v[206:209], v[102:105]
	v_mfma_f32_16x16x32_bf16 v[94:97], v[176:179], v[214:217], v[94:97]
	v_mfma_f32_16x16x32_bf16 v[86:89], v[184:187], v[214:217], v[86:89]
	v_mfma_f32_16x16x32_bf16 v[78:81], v[176:179], v[222:225], v[78:81]
	v_mfma_f32_16x16x32_bf16 v[70:73], v[184:187], v[222:225], v[70:73]
	v_mfma_f32_16x16x32_bf16 v[126:129], v[180:183], v[202:205], v[126:129]
	v_mfma_f32_16x16x32_bf16 v[118:121], v[188:191], v[202:205], v[118:121]
	v_mfma_f32_16x16x32_bf16 v[110:113], v[180:183], v[210:213], v[110:113]
	v_mfma_f32_16x16x32_bf16 v[102:105], v[188:191], v[210:213], v[102:105]
	v_mfma_f32_16x16x32_bf16 v[94:97], v[180:183], v[218:221], v[94:97]
	v_mfma_f32_16x16x32_bf16 v[86:89], v[188:191], v[218:221], v[86:89]
	v_mfma_f32_16x16x32_bf16 v[78:81], v[180:183], v[226:229], v[78:81]
	v_mfma_f32_16x16x32_bf16 v[70:73], v[188:191], v[226:229], v[70:73]
	s_barrier
	s_add_u32 s98, s28, 0x80
	s_addc_u32 s99, s29, 0
	s_add_i32 s34, s59, s38
	s_mov_b32 m0, s34
	ds_read_b128 v[198:201], v166 offset:49152
	ds_read_b128 v[202:205], v166 offset:50176
	ds_read_b128 v[206:209], v166 offset:51200
	ds_read_b128 v[210:213], v166 offset:52224
	ds_read_b128 v[214:217], v166 offset:53248
	ds_read_b128 v[218:221], v166 offset:54272
	ds_read_b128 v[222:225], v166 offset:55296
	ds_read_b128 v[226:229], v166 offset:56320
	global_load_lds_dwordx4 v134, s[98:99]
	s_add_i32 m0, s34, 0x2000
	s_add_u32 s28, s28, 0x80080
	s_addc_u32 s29, s29, 0
	s_add_i32 s34, s60, s38
	global_load_lds_dwordx4 v130, s[98:99]
	s_mov_b32 m0, s34
	s_nop 0
	global_load_lds_dwordx4 v134, s[28:29]
	s_add_i32 m0, s34, 0x2000
	s_nop 0
	global_load_lds_dwordx4 v130, s[28:29]
	s_mov_b32 m0, s48
	s_nop 0
	global_load_lds_dwordx4 v136, s[100:101]
	s_mov_b32 m0, s49
	s_nop 0
	global_load_lds_dwordx4 v132, s[100:101]
	s_waitcnt vmcnt(8)
	s_waitcnt lgkmcnt(0)
	s_barrier
	s_waitcnt lgkmcnt(0)
	v_mfma_f32_16x16x32_bf16 v[58:61], v[152:155], v[198:201], v[58:61]
	v_mfma_f32_16x16x32_bf16 v[50:53], v[168:171], v[198:201], v[50:53]
	v_mfma_f32_16x16x32_bf16 v[42:45], v[152:155], v[206:209], v[42:45]
	v_mfma_f32_16x16x32_bf16 v[34:37], v[168:171], v[206:209], v[34:37]
	v_mfma_f32_16x16x32_bf16 v[26:29], v[152:155], v[214:217], v[26:29]
	v_mfma_f32_16x16x32_bf16 v[18:21], v[168:171], v[214:217], v[18:21]
	v_mfma_f32_16x16x32_bf16 v[10:13], v[152:155], v[222:225], v[10:13]
	v_mfma_f32_16x16x32_bf16 v[6:9], v[168:171], v[222:225], v[6:9]
	v_mfma_f32_16x16x32_bf16 v[58:61], v[156:159], v[202:205], v[58:61]
	v_mfma_f32_16x16x32_bf16 v[50:53], v[172:175], v[202:205], v[50:53]
	v_mfma_f32_16x16x32_bf16 v[42:45], v[156:159], v[210:213], v[42:45]
	v_mfma_f32_16x16x32_bf16 v[34:37], v[172:175], v[210:213], v[34:37]
	v_mfma_f32_16x16x32_bf16 v[26:29], v[156:159], v[218:221], v[26:29]
	v_mfma_f32_16x16x32_bf16 v[18:21], v[172:175], v[218:221], v[18:21]
	v_mfma_f32_16x16x32_bf16 v[10:13], v[156:159], v[226:229], v[10:13]
	v_mfma_f32_16x16x32_bf16 v[6:9], v[172:175], v[226:229], v[6:9]
	v_mfma_f32_16x16x32_bf16 v[62:65], v[176:179], v[198:201], v[62:65]
	v_mfma_f32_16x16x32_bf16 v[54:57], v[184:187], v[198:201], v[54:57]
	v_mfma_f32_16x16x32_bf16 v[46:49], v[176:179], v[206:209], v[46:49]
	v_mfma_f32_16x16x32_bf16 v[38:41], v[184:187], v[206:209], v[38:41]
	v_mfma_f32_16x16x32_bf16 v[30:33], v[176:179], v[214:217], v[30:33]
	v_mfma_f32_16x16x32_bf16 v[22:25], v[184:187], v[214:217], v[22:25]
	v_mfma_f32_16x16x32_bf16 v[14:17], v[176:179], v[222:225], v[14:17]
	v_mfma_f32_16x16x32_bf16 v[2:5], v[184:187], v[222:225], v[2:5]
	v_mfma_f32_16x16x32_bf16 v[62:65], v[180:183], v[202:205], v[62:65]
	v_mfma_f32_16x16x32_bf16 v[54:57], v[188:191], v[202:205], v[54:57]
	v_mfma_f32_16x16x32_bf16 v[46:49], v[180:183], v[210:213], v[46:49]
	v_mfma_f32_16x16x32_bf16 v[38:41], v[188:191], v[210:213], v[38:41]
	v_mfma_f32_16x16x32_bf16 v[30:33], v[180:183], v[218:221], v[30:33]
	v_mfma_f32_16x16x32_bf16 v[22:25], v[188:191], v[218:221], v[22:25]
	v_mfma_f32_16x16x32_bf16 v[14:17], v[180:183], v[226:229], v[14:17]
	v_mfma_f32_16x16x32_bf16 v[2:5], v[188:191], v[226:229], v[2:5]
	s_barrier
	s_add_i32 s57, s57, 2
	s_add_i32 s58, s58, 0x400000
	s_cmp_gt_u32 s57, 29
	s_mov_b64 s[28:29], s[30:31]

; #define PG8_STAGE(bufoff, gbase, voff) do { _Pragma("unroll") for (int _i = 0; _i < 2; ++_i) \
;         __builtin_amdgcn_global_load_lds((const unsigned*)((const char*)(gbase) + (voff)[_i]), (LAS unsigned*)(lds + (bufoff) + ldsw + _i * 8192), 16, 0, 0); } while (0)
; #define PG8_LDA(dst, b, h) do { _Pragma("unroll") for (int m = 0; m < 4; ++m) _Pragma("unroll") for (int k = 0; k < 2; ++k) dst[m][k] = *(const LAS bf16x8*)(lds + PG8_SA(b, h) + aoff + m * 2048 + k * 1024); } while (0)
; #define PG8_LDB(dst, b, h) do { _Pragma("unroll") for (int n = 0; n < 2; ++n) _Pragma("unroll") for (int k = 0; k < 2; ++k) dst[n][k] = *(const LAS bf16x8*)(lds + PG8_SB(b, h) + boff + n * 2048 + k * 1024); } while (0)
; #define PG8_MMA(ai, bj, At, Bt) do { __builtin_amdgcn_s_setprio(1); _Pragma("unroll") for (int m = 0; m < 4; ++m) _Pragma("unroll") for (int n = 0; n < 2; ++n) _Pragma("unroll") for (int k = 0; k < 2; ++k) \
;         acc[ai][bj][m][n] = __builtin_amdgcn_mfma_f32_16x16x32_bf16(Bt[n][k], At[m][k], acc[ai][bj][m][n], 0, 0, 0); __builtin_amdgcn_s_setprio(0); } while (0)
; #define PG8_WAIT_V(n) asm volatile("s_waitcnt vmcnt(" #n ")" ::: "memory")
; #define PG8_WAIT_L(n) asm volatile("s_waitcnt lgkmcnt(" #n ")" ::: "memory")
; template <class Epi, class Sched, int KC, bool ALIGN_EPI = false, bool SP2 = false, bool ATILED = false>
; __device__ __forceinline__ void gemm_phase(LAS unsigned char* lds, const Gemm g, const Sched& S, const Epi& E, int wave_s) {
;     ...
;         const bool has_next = S.next(ui + 1, nxt);
;         const char* nA = has_next ? (const char*)g.A + (size_t)nxt.pm * tstepA : cA; const char* nB = has_next ? (const char*)g.Bt + (size_t)nxt.pn * tstep : cB;
;         for (int t = 0; t < nt; t += 2) {
;             const bool last = (t == nt - 2);
;             const char* a1 = cA + PG8_AOFF(t + 1);
;             const char* a2 = last ? nA : cA + PG8_AOFF(t + 2); const char* b2 = last ? nB : cB + (size_t)(t + 2) * kstep;
;             const char* a3 = a2 + kstep; const char* b3 = b2 + kstep;
;             if (last && has_next) S.a_ready(nxt);
;             if constexpr (SP2) {
;             PG8_LDB(B0, 0, 0); PG8_LDB(B1, 0, 1); PG8_SCHED; PG8_LDA(At, 0, 0); PG8_STAGE(PG8_SA(1, 1), a1 + hstepA, voffA);
;             PG8_WAIT_V(8); PG8_WAIT_L(0); PG8_BAR; PG8_MMA(0, 0, At, B0); PG8_MMA(0, 1, At, B1); PG8_BAR; PG8_SCHED;
.LBB0_317:
	s_add_u32 s50, s22, 0x100
	v_mov_b32_e32 v2, 0
	s_addc_u32 s51, s23, 0
	s_mov_b32 s52, -2
	v_mov_b32_e32 v3, v2
	v_mov_b32_e32 v4, v2
	v_mov_b32_e32 v5, v2
	v_mov_b32_e32 v6, v2
	v_mov_b32_e32 v7, v2
	v_mov_b32_e32 v8, v2
	v_mov_b32_e32 v9, v2
	v_mov_b32_e32 v18, v2
	v_mov_b32_e32 v19, v2
	v_mov_b32_e32 v20, v2
	v_mov_b32_e32 v21, v2
	v_mov_b32_e32 v22, v2
	v_mov_b32_e32 v23, v2
	v_mov_b32_e32 v24, v2
	v_mov_b32_e32 v25, v2
	v_mov_b32_e32 v34, v2
	v_mov_b32_e32 v35, v2
	v_mov_b32_e32 v36, v2
	v_mov_b32_e32 v37, v2
	v_mov_b32_e32 v38, v2
	v_mov_b32_e32 v39, v2
	v_mov_b32_e32 v40, v2
	v_mov_b32_e32 v41, v2
	v_mov_b32_e32 v50, v2
	v_mov_b32_e32 v51, v2
	v_mov_b32_e32 v52, v2
	v_mov_b32_e32 v53, v2
	v_mov_b32_e32 v54, v2
	v_mov_b32_e32 v55, v2
	v_mov_b32_e32 v56, v2
	v_mov_b32_e32 v57, v2
	v_mov_b32_e32 v10, v2
	v_mov_b32_e32 v11, v2
	v_mov_b32_e32 v12, v2
	v_mov_b32_e32 v13, v2
	v_mov_b32_e32 v14, v2
	v_mov_b32_e32 v15, v2
	v_mov_b32_e32 v16, v2
	v_mov_b32_e32 v17, v2
	v_mov_b32_e32 v26, v2
	v_mov_b32_e32 v27, v2
	v_mov_b32_e32 v28, v2
	v_mov_b32_e32 v29, v2
	v_mov_b32_e32 v30, v2
	v_mov_b32_e32 v31, v2
	v_mov_b32_e32 v32, v2
	v_mov_b32_e32 v33, v2
	v_mov_b32_e32 v42, v2
	v_mov_b32_e32 v43, v2
	v_mov_b32_e32 v44, v2
	v_mov_b32_e32 v45, v2
	v_mov_b32_e32 v46, v2
	v_mov_b32_e32 v47, v2
	v_mov_b32_e32 v48, v2
	v_mov_b32_e32 v49, v2
	v_mov_b32_e32 v58, v2
	v_mov_b32_e32 v59, v2
	v_mov_b32_e32 v60, v2
	v_mov_b32_e32 v61, v2
	v_mov_b32_e32 v62, v2
	v_mov_b32_e32 v63, v2
	v_mov_b32_e32 v64, v2
	v_mov_b32_e32 v65, v2
	v_mov_b32_e32 v66, v2
	v_mov_b32_e32 v67, v2
	v_mov_b32_e32 v68, v2
	v_mov_b32_e32 v69, v2
	v_mov_b32_e32 v70, v2
	v_mov_b32_e32 v71, v2
	v_mov_b32_e32 v72, v2
	v_mov_b32_e32 v73, v2
	v_mov_b32_e32 v86, v2
	v_mov_b32_e32 v87, v2
	v_mov_b32_e32 v88, v2
	v_mov_b32_e32 v89, v2
	v_mov_b32_e32 v90, v2
	v_mov_b32_e32 v91, v2
	v_mov_b32_e32 v92, v2
	v_mov_b32_e32 v93, v2
	v_mov_b32_e32 v110, v2
	v_mov_b32_e32 v111, v2
	v_mov_b32_e32 v112, v2
	v_mov_b32_e32 v113, v2
	v_mov_b32_e32 v118, v2
	v_mov_b32_e32 v119, v2
	v_mov_b32_e32 v120, v2
	v_mov_b32_e32 v121, v2
	v_mov_b32_e32 v138, v2
	v_mov_b32_e32 v139, v2
	v_mov_b32_e32 v140, v2
	v_mov_b32_e32 v141, v2
	v_mov_b32_e32 v142, v2
	v_mov_b32_e32 v143, v2
	v_mov_b32_e32 v144, v2
	v_mov_b32_e32 v145, v2
	v_mov_b32_e32 v74, v2
	v_mov_b32_e32 v75, v2
	v_mov_b32_e32 v76, v2
	v_mov_b32_e32 v77, v2
	v_mov_b32_e32 v78, v2
	v_mov_b32_e32 v79, v2
	v_mov_b32_e32 v80, v2
	v_mov_b32_e32 v81, v2
	v_mov_b32_e32 v98, v2
	v_mov_b32_e32 v99, v2
	v_mov_b32_e32 v100, v2
	v_mov_b32_e32 v101, v2
	v_mov_b32_e32 v102, v2
	v_mov_b32_e32 v103, v2
	v_mov_b32_e32 v104, v2
	v_mov_b32_e32 v105, v2
	v_mov_b32_e32 v122, v2
	v_mov_b32_e32 v123, v2
	v_mov_b32_e32 v124, v2
	v_mov_b32_e32 v125, v2
	v_mov_b32_e32 v126, v2
	v_mov_b32_e32 v127, v2
	v_mov_b32_e32 v128, v2
	v_mov_b32_e32 v129, v2
	v_mov_b32_e32 v158, v2
	v_mov_b32_e32 v159, v2
	v_mov_b32_e32 v160, v2
	v_mov_b32_e32 v161, v2
	v_mov_b32_e32 v162, v2
	v_mov_b32_e32 v163, v2
	v_mov_b32_e32 v164, v2
	v_mov_b32_e32 v165, v2
	s_add_u32 s8, s20, 0x100
	s_addc_u32 s9, s21, 0
	s_add_i32 s53, 0, 0x10000
	s_cmpk_eq_i32 s52, 0x54
	s_cselect_b32 s25, s17, s9
	s_cselect_b32 s24, s16, s8
	s_cselect_b32 s23, s11, s51
	s_cselect_b32 s22, s10, s50
	s_add_i32 s54, 0, 0x14000
	v_add_u32_e32 v114, s53, v249
	v_add_u32_e32 v150, s54, v249
	ds_read_b128 v[82:85], v114
	ds_read_b128 v[94:97], v114 offset:1024
	ds_read_b128 v[106:109], v114 offset:2048
	ds_read_b128 v[114:117], v114 offset:3072
	ds_read_b128 v[130:133], v150
	ds_read_b128 v[134:137], v150 offset:1024
	ds_read_b128 v[146:149], v150 offset:2048
	ds_read_b128 v[150:153], v150 offset:3072
	s_add_i32 m0, s36, 0xc000
	ds_read_b128 v[154:157], v251
	ds_read_b128 v[166:169], v251 offset:1024
	ds_read_b128 v[170:173], v251 offset:2048
	ds_read_b128 v[174:177], v251 offset:3072
	ds_read_b128 v[178:181], v251 offset:4096
	ds_read_b128 v[182:185], v251 offset:5120
	ds_read_b128 v[186:189], v251 offset:6144
	ds_read_b128 v[194:197], v251 offset:7168
	global_load_lds_dwordx4 v204, s[20:21]
	s_add_i32 m0, s36, 0xe000
	s_nop 0
	global_load_lds_dwordx4 v202, s[20:21]
	s_waitcnt vmcnt(32)
	s_waitcnt lgkmcnt(0)
	s_barrier
	s_waitcnt lgkmcnt(0)
	v_mfma_f32_16x16x32_bf16 v[162:165], v[82:85], v[154:157], v[162:165]
	v_mfma_f32_16x16x32_bf16 v[158:161], v[106:109], v[154:157], v[158:161]
	v_mfma_f32_16x16x32_bf16 v[126:129], v[82:85], v[170:173], v[126:129]
	v_mfma_f32_16x16x32_bf16 v[122:125], v[106:109], v[170:173], v[122:125]
	v_mfma_f32_16x16x32_bf16 v[102:105], v[82:85], v[178:181], v[102:105]
	v_mfma_f32_16x16x32_bf16 v[98:101], v[106:109], v[178:181], v[98:101]
	v_mfma_f32_16x16x32_bf16 v[78:81], v[82:85], v[186:189], v[78:81]
	v_mfma_f32_16x16x32_bf16 v[74:77], v[106:109], v[186:189], v[74:77]
	v_mfma_f32_16x16x32_bf16 v[162:165], v[94:97], v[166:169], v[162:165]
	v_mfma_f32_16x16x32_bf16 v[158:161], v[114:117], v[166:169], v[158:161]
	v_mfma_f32_16x16x32_bf16 v[126:129], v[94:97], v[174:177], v[126:129]
	v_mfma_f32_16x16x32_bf16 v[122:125], v[114:117], v[174:177], v[122:125]
	v_mfma_f32_16x16x32_bf16 v[102:105], v[94:97], v[182:185], v[102:105]
	v_mfma_f32_16x16x32_bf16 v[98:101], v[114:117], v[182:185], v[98:101]
	v_mfma_f32_16x16x32_bf16 v[78:81], v[94:97], v[194:197], v[78:81]
	v_mfma_f32_16x16x32_bf16 v[74:77], v[114:117], v[194:197], v[74:77]
	v_mfma_f32_16x16x32_bf16 v[142:145], v[130:133], v[154:157], v[142:145]
	v_mfma_f32_16x16x32_bf16 v[138:141], v[146:149], v[154:157], v[138:141]
	v_mfma_f32_16x16x32_bf16 v[118:121], v[130:133], v[170:173], v[118:121]
	v_mfma_f32_16x16x32_bf16 v[110:113], v[146:149], v[170:173], v[110:113]
	v_mfma_f32_16x16x32_bf16 v[90:93], v[130:133], v[178:181], v[90:93]
	v_mfma_f32_16x16x32_bf16 v[86:89], v[146:149], v[178:181], v[86:89]
	v_mfma_f32_16x16x32_bf16 v[70:73], v[130:133], v[186:189], v[70:73]
	v_mfma_f32_16x16x32_bf16 v[66:69], v[146:149], v[186:189], v[66:69]
	v_mfma_f32_16x16x32_bf16 v[142:145], v[134:137], v[166:169], v[142:145]
	v_mfma_f32_16x16x32_bf16 v[138:141], v[150:153], v[166:169], v[138:141]
	v_mfma_f32_16x16x32_bf16 v[118:121], v[134:137], v[174:177], v[118:121]
	v_mfma_f32_16x16x32_bf16 v[110:113], v[150:153], v[174:177], v[110:113]
	v_mfma_f32_16x16x32_bf16 v[90:93], v[134:137], v[182:185], v[90:93]
	v_mfma_f32_16x16x32_bf16 v[86:89], v[150:153], v[182:185], v[86:89]
	v_mfma_f32_16x16x32_bf16 v[70:73], v[134:137], v[194:197], v[70:73]
	v_mfma_f32_16x16x32_bf16 v[66:69], v[150:153], v[194:197], v[66:69]
	s_barrier
; #define PG8_STAGE(bufoff, gbase, voff) do { _Pragma("unroll") for (int _i = 0; _i < 2; ++_i) \
;         __builtin_amdgcn_global_load_lds((const unsigned*)((const char*)(gbase) + (voff)[_i]), (LAS unsigned*)(lds + (bufoff) + ldsw + _i * 8192), 16, 0, 0); } while (0)
; #define PG8_LDA(dst, b, h) do { _Pragma("unroll") for (int m = 0; m < 4; ++m) _Pragma("unroll") for (int k = 0; k < 2; ++k) dst[m][k] = *(const LAS bf16x8*)(lds + PG8_SA(b, h) + aoff + m * 2048 + k * 1024); } while (0)
; #define PG8_LDB(dst, b, h) do { _Pragma("unroll") for (int n = 0; n < 2; ++n) _Pragma("unroll") for (int k = 0; k < 2; ++k) dst[n][k] = *(const LAS bf16x8*)(lds + PG8_SB(b, h) + boff + n * 2048 + k * 1024); } while (0)
; #define PG8_MMA(ai, bj, At, Bt) do { __builtin_amdgcn_s_setprio(1); _Pragma("unroll") for (int m = 0; m < 4; ++m) _Pragma("unroll") for (int n = 0; n < 2; ++n) _Pragma("unroll") for (int k = 0; k < 2; ++k) \
;         acc[ai][bj][m][n] = __builtin_amdgcn_mfma_f32_16x16x32_bf16(Bt[n][k], At[m][k], acc[ai][bj][m][n], 0, 0, 0); __builtin_amdgcn_s_setprio(0); } while (0)
; #define PG8_WAIT_V(n) asm volatile("s_waitcnt vmcnt(" #n ")" ::: "memory")
; #define PG8_WAIT_L(n) asm volatile("s_waitcnt lgkmcnt(" #n ")" ::: "memory")
; #define PG8_BAR __builtin_amdgcn_s_barrier()
; #define PG8_SCHED __builtin_amdgcn_sched_barrier(0)
; template <class Epi, class Sched, int KC, bool ALIGN_EPI = false, bool SP2 = false, bool ATILED = false>
; __device__ __forceinline__ void gemm_phase(LAS unsigned char* lds, const Gemm g, const Sched& S, const Epi& E, int wave_s) {
;     ...
;             PG8_LDA(At, 0, 1); PG8_STAGE(PG8_SB(0, 0), b2, voffB); PG8_STAGE(PG8_SB(0, 1), b2 + hstepB, voffB); PG8_STAGE(PG8_SA(0, 0), a2, voffA);
;             PG8_WAIT_V(8); PG8_WAIT_L(0); PG8_BAR; PG8_MMA(1, 0, At, B0); PG8_MMA(1, 1, At, B1); PG8_BAR; PG8_SCHED;
;             PG8_LDB(B0, 1, 0); PG8_LDB(B1, 1, 1); PG8_SCHED; PG8_LDA(At, 1, 0); PG8_STAGE(PG8_SA(0, 1), a2 + hstepA, voffA);
	s_add_i32 s20, s53, s35
	s_mov_b32 m0, s20
	ds_read_b128 v[154:157], v251 offset:16384
	ds_read_b128 v[166:169], v251 offset:17408
	ds_read_b128 v[170:173], v251 offset:18432
	ds_read_b128 v[174:177], v251 offset:19456
	ds_read_b128 v[178:181], v251 offset:20480
	ds_read_b128 v[182:185], v251 offset:21504
	ds_read_b128 v[186:189], v251 offset:22528
	ds_read_b128 v[194:197], v251 offset:23552
	global_load_lds_dwordx4 v0, s[22:23]
	s_add_i32 m0, s20, 0x2000
	s_add_u32 s20, s22, 0x58000
	s_addc_u32 s21, s23, 0
	s_add_i32 s53, s54, s35
	global_load_lds_dwordx4 v198, s[22:23]
	s_mov_b32 m0, s53
	s_nop 0
	global_load_lds_dwordx4 v0, s[20:21]
	s_add_i32 m0, s53, 0x2000
	s_nop 0
	global_load_lds_dwordx4 v198, s[20:21]
	s_mov_b32 m0, s36
	s_nop 0
	global_load_lds_dwordx4 v190, s[24:25]
	s_mov_b32 m0, s37
	s_nop 0
	global_load_lds_dwordx4 v192, s[24:25]
	s_waitcnt vmcnt(32)
	s_waitcnt lgkmcnt(0)
	s_barrier
	s_waitcnt lgkmcnt(0)
	v_mfma_f32_16x16x32_bf16 v[62:65], v[82:85], v[154:157], v[62:65]
	v_mfma_f32_16x16x32_bf16 v[58:61], v[106:109], v[154:157], v[58:61]
	v_mfma_f32_16x16x32_bf16 v[46:49], v[82:85], v[170:173], v[46:49]
	v_mfma_f32_16x16x32_bf16 v[42:45], v[106:109], v[170:173], v[42:45]
	v_mfma_f32_16x16x32_bf16 v[30:33], v[82:85], v[178:181], v[30:33]
	v_mfma_f32_16x16x32_bf16 v[26:29], v[106:109], v[178:181], v[26:29]
	v_mfma_f32_16x16x32_bf16 v[14:17], v[82:85], v[186:189], v[14:17]
	v_mfma_f32_16x16x32_bf16 v[10:13], v[106:109], v[186:189], v[10:13]
	v_mfma_f32_16x16x32_bf16 v[62:65], v[94:97], v[166:169], v[62:65]
	v_mfma_f32_16x16x32_bf16 v[58:61], v[114:117], v[166:169], v[58:61]
	v_mfma_f32_16x16x32_bf16 v[46:49], v[94:97], v[174:177], v[46:49]
	v_mfma_f32_16x16x32_bf16 v[42:45], v[114:117], v[174:177], v[42:45]
	v_mfma_f32_16x16x32_bf16 v[30:33], v[94:97], v[182:185], v[30:33]
	v_mfma_f32_16x16x32_bf16 v[26:29], v[114:117], v[182:185], v[26:29]
	v_mfma_f32_16x16x32_bf16 v[14:17], v[94:97], v[194:197], v[14:17]
	v_mfma_f32_16x16x32_bf16 v[10:13], v[114:117], v[194:197], v[10:13]
	v_mfma_f32_16x16x32_bf16 v[54:57], v[130:133], v[154:157], v[54:57]
	v_mfma_f32_16x16x32_bf16 v[50:53], v[146:149], v[154:157], v[50:53]
	v_mfma_f32_16x16x32_bf16 v[38:41], v[130:133], v[170:173], v[38:41]
	v_mfma_f32_16x16x32_bf16 v[34:37], v[146:149], v[170:173], v[34:37]
	v_mfma_f32_16x16x32_bf16 v[22:25], v[130:133], v[178:181], v[22:25]
	v_mfma_f32_16x16x32_bf16 v[18:21], v[146:149], v[178:181], v[18:21]
	v_mfma_f32_16x16x32_bf16 v[6:9], v[130:133], v[186:189], v[6:9]
	v_mfma_f32_16x16x32_bf16 v[2:5], v[146:149], v[186:189], v[2:5]
	v_mfma_f32_16x16x32_bf16 v[54:57], v[134:137], v[166:169], v[54:57]
	v_mfma_f32_16x16x32_bf16 v[50:53], v[150:153], v[166:169], v[50:53]
	v_mfma_f32_16x16x32_bf16 v[38:41], v[134:137], v[174:177], v[38:41]
	v_mfma_f32_16x16x32_bf16 v[34:37], v[150:153], v[174:177], v[34:37]
	v_mfma_f32_16x16x32_bf16 v[22:25], v[134:137], v[182:185], v[22:25]
	v_mfma_f32_16x16x32_bf16 v[18:21], v[150:153], v[182:185], v[18:21]
	v_mfma_f32_16x16x32_bf16 v[6:9], v[134:137], v[194:197], v[6:9]
	v_mfma_f32_16x16x32_bf16 v[2:5], v[150:153], v[194:197], v[2:5]
	s_barrier
	s_add_i32 s53, 0, 0x18000
	s_add_i32 s54, 0, 0x1c000
	v_add_u32_e32 v114, s53, v249
	v_add_u32_e32 v150, s54, v249
	ds_read_b128 v[82:85], v114
	ds_read_b128 v[94:97], v114 offset:1024
	ds_read_b128 v[106:109], v114 offset:2048
	ds_read_b128 v[114:117], v114 offset:3072
	ds_read_b128 v[130:133], v150
	ds_read_b128 v[134:137], v150 offset:1024
	ds_read_b128 v[146:149], v150 offset:2048
	ds_read_b128 v[150:153], v150 offset:3072
	s_add_u32 s20, s24, 0x160000
	s_addc_u32 s21, s25, 0
	s_mov_b32 m0, s38
	ds_read_b128 v[154:157], v251 offset:32768
	ds_read_b128 v[166:169], v251 offset:33792
	ds_read_b128 v[170:173], v251 offset:34816
	ds_read_b128 v[174:177], v251 offset:35840
	ds_read_b128 v[178:181], v251 offset:36864
	ds_read_b128 v[182:185], v251 offset:37888
	ds_read_b128 v[186:189], v251 offset:38912
	ds_read_b128 v[194:197], v251 offset:39936
	global_load_lds_dwordx4 v190, s[20:21]
	s_mov_b32 m0, s39
	s_nop 0
	global_load_lds_dwordx4 v192, s[20:21]
	s_waitcnt vmcnt(8)
	s_waitcnt lgkmcnt(0)
	s_barrier
; #define PG8_STAGE(bufoff, gbase, voff) do { _Pragma("unroll") for (int _i = 0; _i < 2; ++_i) \
;         __builtin_amdgcn_global_load_lds((const unsigned*)((const char*)(gbase) + (voff)[_i]), (LAS unsigned*)(lds + (bufoff) + ldsw + _i * 8192), 16, 0, 0); } while (0)
; #define PG8_LDA(dst, b, h) do { _Pragma("unroll") for (int m = 0; m < 4; ++m) _Pragma("unroll") for (int k = 0; k < 2; ++k) dst[m][k] = *(const LAS bf16x8*)(lds + PG8_SA(b, h) + aoff + m * 2048 + k * 1024); } while (0)
; #define PG8_MMA(ai, bj, At, Bt) do { __builtin_amdgcn_s_setprio(1); _Pragma("unroll") for (int m = 0; m < 4; ++m) _Pragma("unroll") for (int n = 0; n < 2; ++n) _Pragma("unroll") for (int k = 0; k < 2; ++k) \
;         acc[ai][bj][m][n] = __builtin_amdgcn_mfma_f32_16x16x32_bf16(Bt[n][k], At[m][k], acc[ai][bj][m][n], 0, 0, 0); __builtin_amdgcn_s_setprio(0); } while (0)
; #define PG8_WAIT_V(n) asm volatile("s_waitcnt vmcnt(" #n ")" ::: "memory")
; #define PG8_WAIT_L(n) asm volatile("s_waitcnt lgkmcnt(" #n ")" ::: "memory")
; #define PG8_BAR __builtin_amdgcn_s_barrier()
; #define PG8_SCHED __builtin_amdgcn_sched_barrier(0)
; template <class Epi, class Sched, int KC, bool ALIGN_EPI = false, bool SP2 = false, bool ATILED = false>
; __device__ __forceinline__ void gemm_phase(LAS unsigned char* lds, const Gemm g, const Sched& S, const Epi& E, int wave_s) {
;     ...
;             PG8_WAIT_V(8); PG8_WAIT_L(0); PG8_BAR; PG8_MMA(0, 0, At, B0); PG8_MMA(0, 1, At, B1); PG8_BAR; PG8_SCHED;
;             PG8_LDA(At, 1, 1); PG8_STAGE(PG8_SB(1, 0), b3, voffB); PG8_STAGE(PG8_SB(1, 1), b3 + hstepB, voffB); PG8_STAGE(PG8_SA(1, 0), a3, voffA);
;             PG8_WAIT_V(8); PG8_WAIT_L(0); PG8_BAR; PG8_MMA(1, 0, At, B0); PG8_MMA(1, 1, At, B1); PG8_BAR; PG8_SCHED;
	s_waitcnt lgkmcnt(0)
	v_mfma_f32_16x16x32_bf16 v[162:165], v[82:85], v[154:157], v[162:165]
	v_mfma_f32_16x16x32_bf16 v[158:161], v[106:109], v[154:157], v[158:161]
	v_mfma_f32_16x16x32_bf16 v[126:129], v[82:85], v[170:173], v[126:129]
	v_mfma_f32_16x16x32_bf16 v[122:125], v[106:109], v[170:173], v[122:125]
	v_mfma_f32_16x16x32_bf16 v[102:105], v[82:85], v[178:181], v[102:105]
	v_mfma_f32_16x16x32_bf16 v[98:101], v[106:109], v[178:181], v[98:101]
	v_mfma_f32_16x16x32_bf16 v[78:81], v[82:85], v[186:189], v[78:81]
	v_mfma_f32_16x16x32_bf16 v[74:77], v[106:109], v[186:189], v[74:77]
	v_mfma_f32_16x16x32_bf16 v[162:165], v[94:97], v[166:169], v[162:165]
	v_mfma_f32_16x16x32_bf16 v[158:161], v[114:117], v[166:169], v[158:161]
	v_mfma_f32_16x16x32_bf16 v[126:129], v[94:97], v[174:177], v[126:129]
	v_mfma_f32_16x16x32_bf16 v[122:125], v[114:117], v[174:177], v[122:125]
	v_mfma_f32_16x16x32_bf16 v[102:105], v[94:97], v[182:185], v[102:105]
	v_mfma_f32_16x16x32_bf16 v[98:101], v[114:117], v[182:185], v[98:101]
	v_mfma_f32_16x16x32_bf16 v[78:81], v[94:97], v[194:197], v[78:81]
	v_mfma_f32_16x16x32_bf16 v[74:77], v[114:117], v[194:197], v[74:77]
	v_mfma_f32_16x16x32_bf16 v[142:145], v[130:133], v[154:157], v[142:145]
	v_mfma_f32_16x16x32_bf16 v[138:141], v[146:149], v[154:157], v[138:141]
	v_mfma_f32_16x16x32_bf16 v[118:121], v[130:133], v[170:173], v[118:121]
	v_mfma_f32_16x16x32_bf16 v[110:113], v[146:149], v[170:173], v[110:113]
	v_mfma_f32_16x16x32_bf16 v[90:93], v[130:133], v[178:181], v[90:93]
	v_mfma_f32_16x16x32_bf16 v[86:89], v[146:149], v[178:181], v[86:89]
	v_mfma_f32_16x16x32_bf16 v[70:73], v[130:133], v[186:189], v[70:73]
	v_mfma_f32_16x16x32_bf16 v[66:69], v[146:149], v[186:189], v[66:69]
	v_mfma_f32_16x16x32_bf16 v[142:145], v[134:137], v[166:169], v[142:145]
	v_mfma_f32_16x16x32_bf16 v[138:141], v[150:153], v[166:169], v[138:141]
	v_mfma_f32_16x16x32_bf16 v[118:121], v[134:137], v[174:177], v[118:121]
	v_mfma_f32_16x16x32_bf16 v[110:113], v[150:153], v[174:177], v[110:113]
	v_mfma_f32_16x16x32_bf16 v[90:93], v[134:137], v[182:185], v[90:93]
	v_mfma_f32_16x16x32_bf16 v[86:89], v[150:153], v[182:185], v[86:89]
	v_mfma_f32_16x16x32_bf16 v[70:73], v[134:137], v[194:197], v[70:73]
	v_mfma_f32_16x16x32_bf16 v[66:69], v[150:153], v[194:197], v[66:69]
	s_barrier
	s_add_u32 s98, s22, 0x80
	s_addc_u32 s99, s23, 0
	s_add_u32 s100, s24, 0x80
	s_addc_u32 s101, s25, 0
	s_add_i32 s20, s53, s35
	s_mov_b32 m0, s20
	ds_read_b128 v[154:157], v251 offset:49152
	ds_read_b128 v[166:169], v251 offset:50176
	ds_read_b128 v[170:173], v251 offset:51200
	ds_read_b128 v[174:177], v251 offset:52224
	ds_read_b128 v[178:181], v251 offset:53248
	ds_read_b128 v[182:185], v251 offset:54272
	ds_read_b128 v[186:189], v251 offset:55296
	ds_read_b128 v[194:197], v251 offset:56320
	global_load_lds_dwordx4 v0, s[98:99]
	s_add_i32 m0, s20, 0x2000
	s_add_u32 s20, s22, 0x58080
	s_addc_u32 s21, s23, 0
	s_add_i32 s22, s54, s35
	global_load_lds_dwordx4 v198, s[98:99]
	s_mov_b32 m0, s22
	s_nop 0
	global_load_lds_dwordx4 v0, s[20:21]
	s_add_i32 m0, s22, 0x2000
	s_nop 0
	global_load_lds_dwordx4 v198, s[20:21]
	s_mov_b32 m0, s43
	s_nop 0
	global_load_lds_dwordx4 v190, s[100:101]
	s_mov_b32 m0, s44
	s_nop 0
	global_load_lds_dwordx4 v192, s[100:101]
	s_waitcnt vmcnt(8)
	s_waitcnt lgkmcnt(0)
	s_barrier
	s_waitcnt lgkmcnt(0)
	v_mfma_f32_16x16x32_bf16 v[62:65], v[82:85], v[154:157], v[62:65]
	v_mfma_f32_16x16x32_bf16 v[58:61], v[106:109], v[154:157], v[58:61]
	v_mfma_f32_16x16x32_bf16 v[46:49], v[82:85], v[170:173], v[46:49]
	v_mfma_f32_16x16x32_bf16 v[42:45], v[106:109], v[170:173], v[42:45]
	v_mfma_f32_16x16x32_bf16 v[30:33], v[82:85], v[178:181], v[30:33]
	v_mfma_f32_16x16x32_bf16 v[26:29], v[106:109], v[178:181], v[26:29]
	v_mfma_f32_16x16x32_bf16 v[14:17], v[82:85], v[186:189], v[14:17]
	v_mfma_f32_16x16x32_bf16 v[10:13], v[106:109], v[186:189], v[10:13]
	v_mfma_f32_16x16x32_bf16 v[62:65], v[94:97], v[166:169], v[62:65]
	v_mfma_f32_16x16x32_bf16 v[58:61], v[114:117], v[166:169], v[58:61]
	v_mfma_f32_16x16x32_bf16 v[46:49], v[94:97], v[174:177], v[46:49]
	v_mfma_f32_16x16x32_bf16 v[42:45], v[114:117], v[174:177], v[42:45]
	v_mfma_f32_16x16x32_bf16 v[30:33], v[94:97], v[182:185], v[30:33]
	v_mfma_f32_16x16x32_bf16 v[26:29], v[114:117], v[182:185], v[26:29]
	v_mfma_f32_16x16x32_bf16 v[14:17], v[94:97], v[194:197], v[14:17]
	v_mfma_f32_16x16x32_bf16 v[10:13], v[114:117], v[194:197], v[10:13]
	v_mfma_f32_16x16x32_bf16 v[54:57], v[130:133], v[154:157], v[54:57]
	v_mfma_f32_16x16x32_bf16 v[50:53], v[146:149], v[154:157], v[50:53]
	v_mfma_f32_16x16x32_bf16 v[38:41], v[130:133], v[170:173], v[38:41]
	v_mfma_f32_16x16x32_bf16 v[34:37], v[146:149], v[170:173], v[34:37]
	v_mfma_f32_16x16x32_bf16 v[22:25], v[130:133], v[178:181], v[22:25]
	v_mfma_f32_16x16x32_bf16 v[18:21], v[146:149], v[178:181], v[18:21]
	v_mfma_f32_16x16x32_bf16 v[6:9], v[130:133], v[186:189], v[6:9]
	v_mfma_f32_16x16x32_bf16 v[2:5], v[146:149], v[186:189], v[2:5]
	v_mfma_f32_16x16x32_bf16 v[54:57], v[134:137], v[166:169], v[54:57]
	v_mfma_f32_16x16x32_bf16 v[50:53], v[150:153], v[166:169], v[50:53]
	v_mfma_f32_16x16x32_bf16 v[38:41], v[134:137], v[174:177], v[38:41]
	v_mfma_f32_16x16x32_bf16 v[34:37], v[150:153], v[174:177], v[34:37]
	v_mfma_f32_16x16x32_bf16 v[22:25], v[134:137], v[182:185], v[22:25]
	v_mfma_f32_16x16x32_bf16 v[18:21], v[150:153], v[182:185], v[18:21]
	v_mfma_f32_16x16x32_bf16 v[6:9], v[134:137], v[194:197], v[6:9]
	v_mfma_f32_16x16x32_bf16 v[2:5], v[150:153], v[194:197], v[2:5]
	s_barrier
	s_add_i32 s52, s52, 2
	s_add_u32 s50, s50, 0x100
	s_addc_u32 s51, s51, 0
	s_cmpk_gt_u32 s52, 0x55
	s_mov_b64 s[20:21], s[8:9]

; #define PG8_STAGE(bufoff, gbase, voff) do { _Pragma("unroll") for (int _i = 0; _i < 2; ++_i) \
;         __builtin_amdgcn_global_load_lds((const unsigned*)((const char*)(gbase) + (voff)[_i]), (LAS unsigned*)(lds + (bufoff) + ldsw + _i * 8192), 16, 0, 0); } while (0)
; #define PG8_LDA(dst, b, h) do { _Pragma("unroll") for (int m = 0; m < 4; ++m) _Pragma("unroll") for (int k = 0; k < 2; ++k) dst[m][k] = *(const LAS bf16x8*)(lds + PG8_SA(b, h) + aoff + m * 2048 + k * 1024); } while (0)
; #define PG8_LDB(dst, b, h) do { _Pragma("unroll") for (int n = 0; n < 2; ++n) _Pragma("unroll") for (int k = 0; k < 2; ++k) dst[n][k] = *(const LAS bf16x8*)(lds + PG8_SB(b, h) + boff + n * 2048 + k * 1024); } while (0)
; #define PG8_MMA(ai, bj, At, Bt) do { __builtin_amdgcn_s_setprio(1); _Pragma("unroll") for (int m = 0; m < 4; ++m) _Pragma("unroll") for (int n = 0; n < 2; ++n) _Pragma("unroll") for (int k = 0; k < 2; ++k) \
;         acc[ai][bj][m][n] = __builtin_amdgcn_mfma_f32_16x16x32_bf16(Bt[n][k], At[m][k], acc[ai][bj][m][n], 0, 0, 0); __builtin_amdgcn_s_setprio(0); } while (0)
; #define PG8_WAIT_V(n) asm volatile("s_waitcnt vmcnt(" #n ")" ::: "memory")
; #define PG8_WAIT_L(n) asm volatile("s_waitcnt lgkmcnt(" #n ")" ::: "memory")
; template <class Epi, class Sched, int KC, bool ALIGN_EPI = false, bool SP2 = false, bool ATILED = false>
; __device__ __forceinline__ void gemm_phase(LAS unsigned char* lds, const Gemm g, const Sched& S, const Epi& E, int wave_s) {
;     ...
;         const bool has_next = S.next(ui + 1, nxt);
;         const char* nA = has_next ? (const char*)g.A + (size_t)nxt.pm * tstepA : cA; const char* nB = has_next ? (const char*)g.Bt + (size_t)nxt.pn * tstep : cB;
;         for (int t = 0; t < nt; t += 2) {
;             const bool last = (t == nt - 2);
;             const char* a1 = cA + PG8_AOFF(t + 1);
;             const char* a2 = last ? nA : cA + PG8_AOFF(t + 2); const char* b2 = last ? nB : cB + (size_t)(t + 2) * kstep;
;             const char* a3 = a2 + kstep; const char* b3 = b2 + kstep;
;             if (last && has_next) S.a_ready(nxt);
;             if constexpr (SP2) {
;             PG8_LDB(B0, 0, 0); PG8_LDB(B1, 0, 1); PG8_SCHED; PG8_LDA(At, 0, 0); PG8_STAGE(PG8_SA(1, 1), a1 + hstepA, voffA);
;             PG8_WAIT_V(8); PG8_WAIT_L(0); PG8_BAR; PG8_MMA(0, 0, At, B0); PG8_MMA(0, 1, At, B1); PG8_BAR; PG8_SCHED;
.LBB0_429:
	s_ashr_i32 s19, s18, 31
	s_lshl_b64 s[20:21], s[18:19], 17
	s_add_u32 s20, s42, s20
	s_addc_u32 s21, s43, s21
	s_and_b64 s[22:23], s[6:7], exec
	s_cselect_b32 s19, s21, s27
	s_cselect_b32 s61, s20, s26
	s_ashr_i32 s17, s16, 31
	s_lshl_b64 s[22:23], s[16:17], 20
	s_add_u32 s22, s44, s22
	s_addc_u32 s23, s45, s23
	s_and_b64 s[30:31], s[6:7], exec
	s_cselect_b32 s17, s23, s29
	s_cselect_b32 s62, s22, s28
	s_add_u32 s63, s28, 0x100
	v_mov_b32_e32 v2, 0
	s_addc_u32 s64, s29, 0
	s_mov_b32 s65, -2
	s_mov_b64 s[28:29], 0
	s_mov_b32 s66, 0x400000
	v_mov_b32_e32 v3, v2
	v_mov_b32_e32 v4, v2
	v_mov_b32_e32 v5, v2
	v_mov_b32_e32 v6, v2
	v_mov_b32_e32 v7, v2
	v_mov_b32_e32 v8, v2
	v_mov_b32_e32 v9, v2
	v_mov_b32_e32 v14, v2
	v_mov_b32_e32 v15, v2
	v_mov_b32_e32 v16, v2
	v_mov_b32_e32 v17, v2
	v_mov_b32_e32 v22, v2
	v_mov_b32_e32 v23, v2
	v_mov_b32_e32 v24, v2
	v_mov_b32_e32 v25, v2
	v_mov_b32_e32 v30, v2
	v_mov_b32_e32 v31, v2
	v_mov_b32_e32 v32, v2
	v_mov_b32_e32 v33, v2
	v_mov_b32_e32 v38, v2
	v_mov_b32_e32 v39, v2
	v_mov_b32_e32 v40, v2
	v_mov_b32_e32 v41, v2
	v_mov_b32_e32 v46, v2
	v_mov_b32_e32 v47, v2
	v_mov_b32_e32 v48, v2
	v_mov_b32_e32 v49, v2
	v_mov_b32_e32 v54, v2
	v_mov_b32_e32 v55, v2
	v_mov_b32_e32 v56, v2
	v_mov_b32_e32 v57, v2
	v_mov_b32_e32 v10, v2
	v_mov_b32_e32 v11, v2
	v_mov_b32_e32 v12, v2
	v_mov_b32_e32 v13, v2
	v_mov_b32_e32 v18, v2
	v_mov_b32_e32 v19, v2
	v_mov_b32_e32 v20, v2
	v_mov_b32_e32 v21, v2
	v_mov_b32_e32 v26, v2
	v_mov_b32_e32 v27, v2
	v_mov_b32_e32 v28, v2
	v_mov_b32_e32 v29, v2
	v_mov_b32_e32 v34, v2
	v_mov_b32_e32 v35, v2
	v_mov_b32_e32 v36, v2
	v_mov_b32_e32 v37, v2
	v_mov_b32_e32 v42, v2
	v_mov_b32_e32 v43, v2
	v_mov_b32_e32 v44, v2
	v_mov_b32_e32 v45, v2
	v_mov_b32_e32 v50, v2
	v_mov_b32_e32 v51, v2
	v_mov_b32_e32 v52, v2
	v_mov_b32_e32 v53, v2
	v_mov_b32_e32 v58, v2
	v_mov_b32_e32 v59, v2
	v_mov_b32_e32 v60, v2
	v_mov_b32_e32 v61, v2
	v_mov_b32_e32 v62, v2
	v_mov_b32_e32 v63, v2
	v_mov_b32_e32 v64, v2
	v_mov_b32_e32 v65, v2
	v_mov_b32_e32 v66, v2
	v_mov_b32_e32 v67, v2
	v_mov_b32_e32 v68, v2
	v_mov_b32_e32 v69, v2
	v_mov_b32_e32 v70, v2
	v_mov_b32_e32 v71, v2
	v_mov_b32_e32 v72, v2
	v_mov_b32_e32 v73, v2
	v_mov_b32_e32 v78, v2
	v_mov_b32_e32 v79, v2
	v_mov_b32_e32 v80, v2
	v_mov_b32_e32 v81, v2
	v_mov_b32_e32 v86, v2
	v_mov_b32_e32 v87, v2
	v_mov_b32_e32 v88, v2
	v_mov_b32_e32 v89, v2
	v_mov_b32_e32 v94, v2
	v_mov_b32_e32 v95, v2
	v_mov_b32_e32 v96, v2
	v_mov_b32_e32 v97, v2
	v_mov_b32_e32 v102, v2
	v_mov_b32_e32 v103, v2
	v_mov_b32_e32 v104, v2
	v_mov_b32_e32 v105, v2
	v_mov_b32_e32 v110, v2
	v_mov_b32_e32 v111, v2
	v_mov_b32_e32 v112, v2
	v_mov_b32_e32 v113, v2
	v_mov_b32_e32 v118, v2
	v_mov_b32_e32 v119, v2
	v_mov_b32_e32 v120, v2
	v_mov_b32_e32 v121, v2
	v_mov_b32_e32 v74, v2
	v_mov_b32_e32 v75, v2
	v_mov_b32_e32 v76, v2
	v_mov_b32_e32 v77, v2
	v_mov_b32_e32 v82, v2
	v_mov_b32_e32 v83, v2
	v_mov_b32_e32 v84, v2
	v_mov_b32_e32 v85, v2
	v_mov_b32_e32 v90, v2
	v_mov_b32_e32 v91, v2
	v_mov_b32_e32 v92, v2
	v_mov_b32_e32 v93, v2
	v_mov_b32_e32 v98, v2
	v_mov_b32_e32 v99, v2
	v_mov_b32_e32 v100, v2
	v_mov_b32_e32 v101, v2
	v_mov_b32_e32 v106, v2
	v_mov_b32_e32 v107, v2
	v_mov_b32_e32 v108, v2
	v_mov_b32_e32 v109, v2
	v_mov_b32_e32 v114, v2
	v_mov_b32_e32 v115, v2
	v_mov_b32_e32 v116, v2
	v_mov_b32_e32 v117, v2
	v_mov_b32_e32 v122, v2
	v_mov_b32_e32 v123, v2
	v_mov_b32_e32 v124, v2
	v_mov_b32_e32 v125, v2
	v_mov_b32_e32 v126, v2
	v_mov_b32_e32 v127, v2
	v_mov_b32_e32 v128, v2
	v_mov_b32_e32 v129, v2
	s_add_i32 s30, s66, 0xffc00000
	s_and_b32 s30, s30, 0x3800000
	s_and_b32 s31, s28, 0x100
	s_or_b32 s67, s31, s30
	s_and_b32 s34, s66, 0x7800000
	s_add_u32 s30, s28, 0x100
	s_addc_u32 s31, s29, 0
	s_and_b32 s35, s30, 0x100
	s_or_b32 s34, s34, s35
	s_add_u32 s34, s26, s34
	s_addc_u32 s35, s27, 0
	s_add_u32 s28, s63, s28
	s_addc_u32 s29, s64, s29
	s_add_i32 s70, 0, 0x10000
	s_cmp_eq_u32 s65, 28
	s_cselect_b32 s35, s19, s35
	s_cselect_b32 s34, s61, s34
	v_add_u32_e32 v139, s70, v165
	s_cselect_b32 s29, s17, s29
	s_cselect_b32 s28, s62, s28
	s_add_i32 s71, 0, 0x14000
	ds_read_b128 v[152:155], v139
	ds_read_b128 v[160:163], v139 offset:1024
	ds_read_b128 v[174:177], v139 offset:2048
	ds_read_b128 v[178:181], v139 offset:3072
	v_add_u32_e32 v139, s71, v165
	ds_read_b128 v[182:185], v139
	ds_read_b128 v[186:189], v139 offset:1024
	ds_read_b128 v[190:193], v139 offset:2048
	ds_read_b128 v[194:197], v139 offset:3072
	s_add_u32 s67, s26, s67
	s_addc_u32 s69, s27, 0
	s_add_u32 s68, s67, 0x10080
	s_addc_u32 s69, s69, 0
	s_add_i32 m0, s25, 0xc000
	ds_read_b128 v[198:201], v173
	ds_read_b128 v[202:205], v173 offset:1024
	ds_read_b128 v[206:209], v173 offset:2048
	ds_read_b128 v[210:213], v173 offset:3072
	ds_read_b128 v[214:217], v173 offset:4096
	ds_read_b128 v[218:221], v173 offset:5120
	ds_read_b128 v[222:225], v173 offset:6144
	ds_read_b128 v[226:229], v173 offset:7168
	global_load_lds_dwordx4 v136, s[68:69]
	s_add_i32 m0, s25, 0xe000
	s_nop 0
	global_load_lds_dwordx4 v132, s[68:69]
	s_waitcnt vmcnt(24)
	s_waitcnt lgkmcnt(0)
	s_barrier
; #define PG8_STAGE(bufoff, gbase, voff) do { _Pragma("unroll") for (int _i = 0; _i < 2; ++_i) \
;         __builtin_amdgcn_global_load_lds((const unsigned*)((const char*)(gbase) + (voff)[_i]), (LAS unsigned*)(lds + (bufoff) + ldsw + _i * 8192), 16, 0, 0); } while (0)
; #define PG8_LDA(dst, b, h) do { _Pragma("unroll") for (int m = 0; m < 4; ++m) _Pragma("unroll") for (int k = 0; k < 2; ++k) dst[m][k] = *(const LAS bf16x8*)(lds + PG8_SA(b, h) + aoff + m * 2048 + k * 1024); } while (0)
; #define PG8_MMA(ai, bj, At, Bt) do { __builtin_amdgcn_s_setprio(1); _Pragma("unroll") for (int m = 0; m < 4; ++m) _Pragma("unroll") for (int n = 0; n < 2; ++n) _Pragma("unroll") for (int k = 0; k < 2; ++k) \
;         acc[ai][bj][m][n] = __builtin_amdgcn_mfma_f32_16x16x32_bf16(Bt[n][k], At[m][k], acc[ai][bj][m][n], 0, 0, 0); __builtin_amdgcn_s_setprio(0); } while (0)
; #define PG8_WAIT_V(n) asm volatile("s_waitcnt vmcnt(" #n ")" ::: "memory")
; #define PG8_WAIT_L(n) asm volatile("s_waitcnt lgkmcnt(" #n ")" ::: "memory")
; #define PG8_BAR __builtin_amdgcn_s_barrier()
; #define PG8_SCHED __builtin_amdgcn_sched_barrier(0)
; template <class Epi, class Sched, int KC, bool ALIGN_EPI = false, bool SP2 = false, bool ATILED = false>
; __device__ __forceinline__ void gemm_phase(LAS unsigned char* lds, const Gemm g, const Sched& S, const Epi& E, int wave_s) {
;     ...
;             PG8_WAIT_V(8); PG8_WAIT_L(0); PG8_BAR; PG8_MMA(0, 0, At, B0); PG8_MMA(0, 1, At, B1); PG8_BAR; PG8_SCHED;
;             PG8_LDA(At, 0, 1); PG8_STAGE(PG8_SB(0, 0), b2, voffB); PG8_STAGE(PG8_SB(0, 1), b2 + hstepB, voffB); PG8_STAGE(PG8_SA(0, 0), a2, voffA);
;             PG8_WAIT_V(8); PG8_WAIT_L(0); PG8_BAR; PG8_MMA(1, 0, At, B0); PG8_MMA(1, 1, At, B1); PG8_BAR; PG8_SCHED;
	s_waitcnt lgkmcnt(0)
	v_mfma_f32_16x16x32_bf16 v[126:129], v[152:155], v[198:201], v[126:129]
	v_mfma_f32_16x16x32_bf16 v[122:125], v[174:177], v[198:201], v[122:125]
	v_mfma_f32_16x16x32_bf16 v[114:117], v[152:155], v[206:209], v[114:117]
	v_mfma_f32_16x16x32_bf16 v[106:109], v[174:177], v[206:209], v[106:109]
	v_mfma_f32_16x16x32_bf16 v[98:101], v[152:155], v[214:217], v[98:101]
	v_mfma_f32_16x16x32_bf16 v[90:93], v[174:177], v[214:217], v[90:93]
	v_mfma_f32_16x16x32_bf16 v[82:85], v[152:155], v[222:225], v[82:85]
	v_mfma_f32_16x16x32_bf16 v[74:77], v[174:177], v[222:225], v[74:77]
	v_mfma_f32_16x16x32_bf16 v[126:129], v[160:163], v[202:205], v[126:129]
	v_mfma_f32_16x16x32_bf16 v[122:125], v[178:181], v[202:205], v[122:125]
	v_mfma_f32_16x16x32_bf16 v[114:117], v[160:163], v[210:213], v[114:117]
	v_mfma_f32_16x16x32_bf16 v[106:109], v[178:181], v[210:213], v[106:109]
	v_mfma_f32_16x16x32_bf16 v[98:101], v[160:163], v[218:221], v[98:101]
	v_mfma_f32_16x16x32_bf16 v[90:93], v[178:181], v[218:221], v[90:93]
	v_mfma_f32_16x16x32_bf16 v[82:85], v[160:163], v[226:229], v[82:85]
	v_mfma_f32_16x16x32_bf16 v[74:77], v[178:181], v[226:229], v[74:77]
	v_mfma_f32_16x16x32_bf16 v[118:121], v[182:185], v[198:201], v[118:121]
	v_mfma_f32_16x16x32_bf16 v[110:113], v[190:193], v[198:201], v[110:113]
	v_mfma_f32_16x16x32_bf16 v[102:105], v[182:185], v[206:209], v[102:105]
	v_mfma_f32_16x16x32_bf16 v[94:97], v[190:193], v[206:209], v[94:97]
	v_mfma_f32_16x16x32_bf16 v[86:89], v[182:185], v[214:217], v[86:89]
	v_mfma_f32_16x16x32_bf16 v[78:81], v[190:193], v[214:217], v[78:81]
	v_mfma_f32_16x16x32_bf16 v[70:73], v[182:185], v[222:225], v[70:73]
	v_mfma_f32_16x16x32_bf16 v[66:69], v[190:193], v[222:225], v[66:69]
	v_mfma_f32_16x16x32_bf16 v[118:121], v[186:189], v[202:205], v[118:121]
	v_mfma_f32_16x16x32_bf16 v[110:113], v[194:197], v[202:205], v[110:113]
	v_mfma_f32_16x16x32_bf16 v[102:105], v[186:189], v[210:213], v[102:105]
	v_mfma_f32_16x16x32_bf16 v[94:97], v[194:197], v[210:213], v[94:97]
	v_mfma_f32_16x16x32_bf16 v[86:89], v[186:189], v[218:221], v[86:89]
	v_mfma_f32_16x16x32_bf16 v[78:81], v[194:197], v[218:221], v[78:81]
	v_mfma_f32_16x16x32_bf16 v[70:73], v[186:189], v[226:229], v[70:73]
	v_mfma_f32_16x16x32_bf16 v[66:69], v[194:197], v[226:229], v[66:69]
	s_barrier
	s_add_u32 s100, s34, 0x80
	s_addc_u32 s101, s35, 0
	s_add_i32 s67, s70, s41
	s_mov_b32 m0, s67
	ds_read_b128 v[198:201], v173 offset:16384
	ds_read_b128 v[202:205], v173 offset:17408
	ds_read_b128 v[206:209], v173 offset:18432
	ds_read_b128 v[210:213], v173 offset:19456
	ds_read_b128 v[214:217], v173 offset:20480
	ds_read_b128 v[218:221], v173 offset:21504
	ds_read_b128 v[222:225], v173 offset:22528
	ds_read_b128 v[226:229], v173 offset:23552
	global_load_lds_dwordx4 v134, s[28:29]
	s_add_i32 m0, s67, 0x2000
	s_add_u32 s68, s28, 0x80000
	s_addc_u32 s69, s29, 0
	s_add_i32 s67, s71, s41
	global_load_lds_dwordx4 v130, s[28:29]
	s_mov_b32 m0, s67
	s_nop 0
	global_load_lds_dwordx4 v134, s[68:69]
	s_add_i32 m0, s67, 0x2000
	s_nop 0
	global_load_lds_dwordx4 v130, s[68:69]
	s_mov_b32 m0, s25
	s_nop 0
	global_load_lds_dwordx4 v136, s[34:35]
	s_mov_b32 m0, s52
	s_nop 0
	global_load_lds_dwordx4 v132, s[34:35]
	s_waitcnt vmcnt(24)
	s_waitcnt lgkmcnt(0)
	s_barrier
	s_waitcnt lgkmcnt(0)
	v_mfma_f32_16x16x32_bf16 v[62:65], v[152:155], v[198:201], v[62:65]
	v_mfma_f32_16x16x32_bf16 v[58:61], v[174:177], v[198:201], v[58:61]
	v_mfma_f32_16x16x32_bf16 v[50:53], v[152:155], v[206:209], v[50:53]
	v_mfma_f32_16x16x32_bf16 v[42:45], v[174:177], v[206:209], v[42:45]
	v_mfma_f32_16x16x32_bf16 v[34:37], v[152:155], v[214:217], v[34:37]
	v_mfma_f32_16x16x32_bf16 v[26:29], v[174:177], v[214:217], v[26:29]
	v_mfma_f32_16x16x32_bf16 v[18:21], v[152:155], v[222:225], v[18:21]
	v_mfma_f32_16x16x32_bf16 v[10:13], v[174:177], v[222:225], v[10:13]
	v_mfma_f32_16x16x32_bf16 v[62:65], v[160:163], v[202:205], v[62:65]
	v_mfma_f32_16x16x32_bf16 v[58:61], v[178:181], v[202:205], v[58:61]
	v_mfma_f32_16x16x32_bf16 v[50:53], v[160:163], v[210:213], v[50:53]
	v_mfma_f32_16x16x32_bf16 v[42:45], v[178:181], v[210:213], v[42:45]
	v_mfma_f32_16x16x32_bf16 v[34:37], v[160:163], v[218:221], v[34:37]
	v_mfma_f32_16x16x32_bf16 v[26:29], v[178:181], v[218:221], v[26:29]
	v_mfma_f32_16x16x32_bf16 v[18:21], v[160:163], v[226:229], v[18:21]
	v_mfma_f32_16x16x32_bf16 v[10:13], v[178:181], v[226:229], v[10:13]
	v_mfma_f32_16x16x32_bf16 v[54:57], v[182:185], v[198:201], v[54:57]
	v_mfma_f32_16x16x32_bf16 v[46:49], v[190:193], v[198:201], v[46:49]
	v_mfma_f32_16x16x32_bf16 v[38:41], v[182:185], v[206:209], v[38:41]
	v_mfma_f32_16x16x32_bf16 v[30:33], v[190:193], v[206:209], v[30:33]
	v_mfma_f32_16x16x32_bf16 v[22:25], v[182:185], v[214:217], v[22:25]
	v_mfma_f32_16x16x32_bf16 v[14:17], v[190:193], v[214:217], v[14:17]
	v_mfma_f32_16x16x32_bf16 v[6:9], v[182:185], v[222:225], v[6:9]
	v_mfma_f32_16x16x32_bf16 v[2:5], v[190:193], v[222:225], v[2:5]
	v_mfma_f32_16x16x32_bf16 v[54:57], v[186:189], v[202:205], v[54:57]
	v_mfma_f32_16x16x32_bf16 v[46:49], v[194:197], v[202:205], v[46:49]
	v_mfma_f32_16x16x32_bf16 v[38:41], v[186:189], v[210:213], v[38:41]
	v_mfma_f32_16x16x32_bf16 v[30:33], v[194:197], v[210:213], v[30:33]
	v_mfma_f32_16x16x32_bf16 v[22:25], v[186:189], v[218:221], v[22:25]
	v_mfma_f32_16x16x32_bf16 v[14:17], v[194:197], v[218:221], v[14:17]
	v_mfma_f32_16x16x32_bf16 v[6:9], v[186:189], v[226:229], v[6:9]
	v_mfma_f32_16x16x32_bf16 v[2:5], v[194:197], v[226:229], v[2:5]
	s_barrier
; #define PG8_STAGE(bufoff, gbase, voff) do { _Pragma("unroll") for (int _i = 0; _i < 2; ++_i) \
;         __builtin_amdgcn_global_load_lds((const unsigned*)((const char*)(gbase) + (voff)[_i]), (LAS unsigned*)(lds + (bufoff) + ldsw + _i * 8192), 16, 0, 0); } while (0)
; #define PG8_LDA(dst, b, h) do { _Pragma("unroll") for (int m = 0; m < 4; ++m) _Pragma("unroll") for (int k = 0; k < 2; ++k) dst[m][k] = *(const LAS bf16x8*)(lds + PG8_SA(b, h) + aoff + m * 2048 + k * 1024); } while (0)
; #define PG8_LDB(dst, b, h) do { _Pragma("unroll") for (int n = 0; n < 2; ++n) _Pragma("unroll") for (int k = 0; k < 2; ++k) dst[n][k] = *(const LAS bf16x8*)(lds + PG8_SB(b, h) + boff + n * 2048 + k * 1024); } while (0)
; #define PG8_MMA(ai, bj, At, Bt) do { __builtin_amdgcn_s_setprio(1); _Pragma("unroll") for (int m = 0; m < 4; ++m) _Pragma("unroll") for (int n = 0; n < 2; ++n) _Pragma("unroll") for (int k = 0; k < 2; ++k) \
;         acc[ai][bj][m][n] = __builtin_amdgcn_mfma_f32_16x16x32_bf16(Bt[n][k], At[m][k], acc[ai][bj][m][n], 0, 0, 0); __builtin_amdgcn_s_setprio(0); } while (0)
; #define PG8_WAIT_V(n) asm volatile("s_waitcnt vmcnt(" #n ")" ::: "memory")
; #define PG8_WAIT_L(n) asm volatile("s_waitcnt lgkmcnt(" #n ")" ::: "memory")
; #define PG8_BAR __builtin_amdgcn_s_barrier()
; #define PG8_SCHED __builtin_amdgcn_sched_barrier(0)
; template <class Epi, class Sched, int KC, bool ALIGN_EPI = false, bool SP2 = false, bool ATILED = false>
; __device__ __forceinline__ void gemm_phase(LAS unsigned char* lds, const Gemm g, const Sched& S, const Epi& E, int wave_s) {
;     ...
;             PG8_LDB(B0, 1, 0); PG8_LDB(B1, 1, 1); PG8_SCHED; PG8_LDA(At, 1, 0); PG8_STAGE(PG8_SA(0, 1), a2 + hstepA, voffA);
;             PG8_WAIT_V(8); PG8_WAIT_L(0); PG8_BAR; PG8_MMA(0, 0, At, B0); PG8_MMA(0, 1, At, B1); PG8_BAR; PG8_SCHED;
;             PG8_LDA(At, 1, 1); PG8_STAGE(PG8_SB(1, 0), b3, voffB); PG8_STAGE(PG8_SB(1, 1), b3 + hstepB, voffB); PG8_STAGE(PG8_SA(1, 0), a3, voffA);
;             PG8_WAIT_V(8); PG8_WAIT_L(0); PG8_BAR; PG8_MMA(1, 0, At, B0); PG8_MMA(1, 1, At, B1); PG8_BAR; PG8_SCHED;
	s_add_i32 s67, 0, 0x18000
	v_add_u32_e32 v139, s67, v165
	s_add_i32 s68, 0, 0x1c000
	ds_read_b128 v[152:155], v139
	ds_read_b128 v[160:163], v139 offset:1024
	ds_read_b128 v[174:177], v139 offset:2048
	ds_read_b128 v[178:181], v139 offset:3072
	v_add_u32_e32 v139, s68, v165
	ds_read_b128 v[182:185], v139
	ds_read_b128 v[186:189], v139 offset:1024
	ds_read_b128 v[190:193], v139 offset:2048
	ds_read_b128 v[194:197], v139 offset:3072
	s_add_u32 s34, s34, 0x10000
	s_addc_u32 s35, s35, 0
	s_mov_b32 m0, s53
	ds_read_b128 v[198:201], v173 offset:32768
	ds_read_b128 v[202:205], v173 offset:33792
	ds_read_b128 v[206:209], v173 offset:34816
	ds_read_b128 v[210:213], v173 offset:35840
	ds_read_b128 v[214:217], v173 offset:36864
	ds_read_b128 v[218:221], v173 offset:37888
	ds_read_b128 v[222:225], v173 offset:38912
	ds_read_b128 v[226:229], v173 offset:39936
	global_load_lds_dwordx4 v136, s[34:35]
	s_mov_b32 m0, s54
	s_nop 0
	global_load_lds_dwordx4 v132, s[34:35]
	s_waitcnt vmcnt(8)
	s_waitcnt lgkmcnt(0)
	s_barrier
	s_waitcnt lgkmcnt(0)
	v_mfma_f32_16x16x32_bf16 v[126:129], v[152:155], v[198:201], v[126:129]
	v_mfma_f32_16x16x32_bf16 v[122:125], v[174:177], v[198:201], v[122:125]
	v_mfma_f32_16x16x32_bf16 v[114:117], v[152:155], v[206:209], v[114:117]
	v_mfma_f32_16x16x32_bf16 v[106:109], v[174:177], v[206:209], v[106:109]
	v_mfma_f32_16x16x32_bf16 v[98:101], v[152:155], v[214:217], v[98:101]
	v_mfma_f32_16x16x32_bf16 v[90:93], v[174:177], v[214:217], v[90:93]
	v_mfma_f32_16x16x32_bf16 v[82:85], v[152:155], v[222:225], v[82:85]
	v_mfma_f32_16x16x32_bf16 v[74:77], v[174:177], v[222:225], v[74:77]
	v_mfma_f32_16x16x32_bf16 v[126:129], v[160:163], v[202:205], v[126:129]
	v_mfma_f32_16x16x32_bf16 v[122:125], v[178:181], v[202:205], v[122:125]
	v_mfma_f32_16x16x32_bf16 v[114:117], v[160:163], v[210:213], v[114:117]
	v_mfma_f32_16x16x32_bf16 v[106:109], v[178:181], v[210:213], v[106:109]
	v_mfma_f32_16x16x32_bf16 v[98:101], v[160:163], v[218:221], v[98:101]
	v_mfma_f32_16x16x32_bf16 v[90:93], v[178:181], v[218:221], v[90:93]
	v_mfma_f32_16x16x32_bf16 v[82:85], v[160:163], v[226:229], v[82:85]
	v_mfma_f32_16x16x32_bf16 v[74:77], v[178:181], v[226:229], v[74:77]
	v_mfma_f32_16x16x32_bf16 v[118:121], v[182:185], v[198:201], v[118:121]
	v_mfma_f32_16x16x32_bf16 v[110:113], v[190:193], v[198:201], v[110:113]
	v_mfma_f32_16x16x32_bf16 v[102:105], v[182:185], v[206:209], v[102:105]
	v_mfma_f32_16x16x32_bf16 v[94:97], v[190:193], v[206:209], v[94:97]
	v_mfma_f32_16x16x32_bf16 v[86:89], v[182:185], v[214:217], v[86:89]
	v_mfma_f32_16x16x32_bf16 v[78:81], v[190:193], v[214:217], v[78:81]
	v_mfma_f32_16x16x32_bf16 v[70:73], v[182:185], v[222:225], v[70:73]
	v_mfma_f32_16x16x32_bf16 v[66:69], v[190:193], v[222:225], v[66:69]
	v_mfma_f32_16x16x32_bf16 v[118:121], v[186:189], v[202:205], v[118:121]
	v_mfma_f32_16x16x32_bf16 v[110:113], v[194:197], v[202:205], v[110:113]
	v_mfma_f32_16x16x32_bf16 v[102:105], v[186:189], v[210:213], v[102:105]
	v_mfma_f32_16x16x32_bf16 v[94:97], v[194:197], v[210:213], v[94:97]
	v_mfma_f32_16x16x32_bf16 v[86:89], v[186:189], v[218:221], v[86:89]
	v_mfma_f32_16x16x32_bf16 v[78:81], v[194:197], v[218:221], v[78:81]
	v_mfma_f32_16x16x32_bf16 v[70:73], v[186:189], v[226:229], v[70:73]
	v_mfma_f32_16x16x32_bf16 v[66:69], v[194:197], v[226:229], v[66:69]
	s_barrier
	s_add_u32 s98, s28, 0x80
	s_addc_u32 s99, s29, 0
	s_add_i32 s34, s67, s41
	s_mov_b32 m0, s34
	ds_read_b128 v[198:201], v173 offset:49152
	ds_read_b128 v[202:205], v173 offset:50176
	ds_read_b128 v[206:209], v173 offset:51200
	ds_read_b128 v[210:213], v173 offset:52224
	ds_read_b128 v[214:217], v173 offset:53248
	ds_read_b128 v[218:221], v173 offset:54272
	ds_read_b128 v[222:225], v173 offset:55296
	ds_read_b128 v[226:229], v173 offset:56320
	global_load_lds_dwordx4 v134, s[98:99]
	s_add_i32 m0, s34, 0x2000
	s_add_u32 s28, s28, 0x80080
	s_addc_u32 s29, s29, 0
	s_add_i32 s34, s68, s41
	global_load_lds_dwordx4 v130, s[98:99]
	s_mov_b32 m0, s34
	s_nop 0
	global_load_lds_dwordx4 v134, s[28:29]
	s_add_i32 m0, s34, 0x2000
	s_nop 0
	global_load_lds_dwordx4 v130, s[28:29]
	s_mov_b32 m0, s55
	s_nop 0
	global_load_lds_dwordx4 v136, s[100:101]
	s_mov_b32 m0, s56
	s_nop 0
	global_load_lds_dwordx4 v132, s[100:101]
	s_waitcnt vmcnt(8)
	s_waitcnt lgkmcnt(0)
	s_barrier
	s_waitcnt lgkmcnt(0)
	v_mfma_f32_16x16x32_bf16 v[62:65], v[152:155], v[198:201], v[62:65]
	v_mfma_f32_16x16x32_bf16 v[58:61], v[174:177], v[198:201], v[58:61]
	v_mfma_f32_16x16x32_bf16 v[50:53], v[152:155], v[206:209], v[50:53]
	v_mfma_f32_16x16x32_bf16 v[42:45], v[174:177], v[206:209], v[42:45]
	v_mfma_f32_16x16x32_bf16 v[34:37], v[152:155], v[214:217], v[34:37]
	v_mfma_f32_16x16x32_bf16 v[26:29], v[174:177], v[214:217], v[26:29]
	v_mfma_f32_16x16x32_bf16 v[18:21], v[152:155], v[222:225], v[18:21]
	v_mfma_f32_16x16x32_bf16 v[10:13], v[174:177], v[222:225], v[10:13]
	v_mfma_f32_16x16x32_bf16 v[62:65], v[160:163], v[202:205], v[62:65]
	v_mfma_f32_16x16x32_bf16 v[58:61], v[178:181], v[202:205], v[58:61]
	v_mfma_f32_16x16x32_bf16 v[50:53], v[160:163], v[210:213], v[50:53]
	v_mfma_f32_16x16x32_bf16 v[42:45], v[178:181], v[210:213], v[42:45]
	v_mfma_f32_16x16x32_bf16 v[34:37], v[160:163], v[218:221], v[34:37]
	v_mfma_f32_16x16x32_bf16 v[26:29], v[178:181], v[218:221], v[26:29]
	v_mfma_f32_16x16x32_bf16 v[18:21], v[160:163], v[226:229], v[18:21]
	v_mfma_f32_16x16x32_bf16 v[10:13], v[178:181], v[226:229], v[10:13]
	v_mfma_f32_16x16x32_bf16 v[54:57], v[182:185], v[198:201], v[54:57]
	v_mfma_f32_16x16x32_bf16 v[46:49], v[190:193], v[198:201], v[46:49]
	v_mfma_f32_16x16x32_bf16 v[38:41], v[182:185], v[206:209], v[38:41]
	v_mfma_f32_16x16x32_bf16 v[30:33], v[190:193], v[206:209], v[30:33]
	v_mfma_f32_16x16x32_bf16 v[22:25], v[182:185], v[214:217], v[22:25]
	v_mfma_f32_16x16x32_bf16 v[14:17], v[190:193], v[214:217], v[14:17]
	v_mfma_f32_16x16x32_bf16 v[6:9], v[182:185], v[222:225], v[6:9]
	v_mfma_f32_16x16x32_bf16 v[2:5], v[190:193], v[222:225], v[2:5]
	v_mfma_f32_16x16x32_bf16 v[54:57], v[186:189], v[202:205], v[54:57]
	v_mfma_f32_16x16x32_bf16 v[46:49], v[194:197], v[202:205], v[46:49]
	v_mfma_f32_16x16x32_bf16 v[38:41], v[186:189], v[210:213], v[38:41]
	v_mfma_f32_16x16x32_bf16 v[30:33], v[194:197], v[210:213], v[30:33]
	v_mfma_f32_16x16x32_bf16 v[22:25], v[186:189], v[218:221], v[22:25]
	v_mfma_f32_16x16x32_bf16 v[14:17], v[194:197], v[218:221], v[14:17]
	v_mfma_f32_16x16x32_bf16 v[6:9], v[186:189], v[226:229], v[6:9]
	v_mfma_f32_16x16x32_bf16 v[2:5], v[194:197], v[226:229], v[2:5]
	s_barrier
	s_add_i32 s65, s65, 2
	s_add_i32 s66, s66, 0x400000
	s_cmp_gt_u32 s65, 29
	s_mov_b64 s[28:29], s[30:31]

; #define PG8_STAGE(bufoff, gbase, voff) do { _Pragma("unroll") for (int _i = 0; _i < 2; ++_i) \
;         __builtin_amdgcn_global_load_lds((const unsigned*)((const char*)(gbase) + (voff)[_i]), (LAS unsigned*)(lds + (bufoff) + ldsw + _i * 8192), 16, 0, 0); } while (0)
; #define PG8_LDA(dst, b, h) do { _Pragma("unroll") for (int m = 0; m < 4; ++m) _Pragma("unroll") for (int k = 0; k < 2; ++k) dst[m][k] = *(const LAS bf16x8*)(lds + PG8_SA(b, h) + aoff + m * 2048 + k * 1024); } while (0)
; #define PG8_LDB(dst, b, h) do { _Pragma("unroll") for (int n = 0; n < 2; ++n) _Pragma("unroll") for (int k = 0; k < 2; ++k) dst[n][k] = *(const LAS bf16x8*)(lds + PG8_SB(b, h) + boff + n * 2048 + k * 1024); } while (0)
; #define PG8_MMA(ai, bj, At, Bt) do { __builtin_amdgcn_s_setprio(1); _Pragma("unroll") for (int m = 0; m < 4; ++m) _Pragma("unroll") for (int n = 0; n < 2; ++n) _Pragma("unroll") for (int k = 0; k < 2; ++k) \
;         acc[ai][bj][m][n] = __builtin_amdgcn_mfma_f32_16x16x32_bf16(Bt[n][k], At[m][k], acc[ai][bj][m][n], 0, 0, 0); __builtin_amdgcn_s_setprio(0); } while (0)
; #define PG8_WAIT_V(n) asm volatile("s_waitcnt vmcnt(" #n ")" ::: "memory")
; #define PG8_WAIT_L(n) asm volatile("s_waitcnt lgkmcnt(" #n ")" ::: "memory")
; template <class Epi, class Sched, int KC, bool ALIGN_EPI = false, bool SP2 = false, bool ATILED = false>
; __device__ __forceinline__ void gemm_phase(LAS unsigned char* lds, const Gemm g, const Sched& S, const Epi& E, int wave_s) {
;     ...
;         const bool has_next = S.next(ui + 1, nxt);
;         const char* nA = has_next ? (const char*)g.A + (size_t)nxt.pm * tstepA : cA; const char* nB = has_next ? (const char*)g.Bt + (size_t)nxt.pn * tstep : cB;
;         for (int t = 0; t < nt; t += 2) {
;             const bool last = (t == nt - 2);
;             const char* a1 = cA + PG8_AOFF(t + 1);
;             const char* a2 = last ? nA : cA + PG8_AOFF(t + 2); const char* b2 = last ? nB : cB + (size_t)(t + 2) * kstep;
;             const char* a3 = a2 + kstep; const char* b3 = b2 + kstep;
;             if (last && has_next) S.a_ready(nxt);
;             if constexpr (SP2) {
;             PG8_LDB(B0, 0, 0); PG8_LDB(B1, 0, 1); PG8_SCHED; PG8_LDA(At, 0, 0); PG8_STAGE(PG8_SA(1, 1), a1 + hstepA, voffA);
;             PG8_WAIT_V(8); PG8_WAIT_L(0); PG8_BAR; PG8_MMA(0, 0, At, B0); PG8_MMA(0, 1, At, B1); PG8_BAR; PG8_SCHED;
.LBB0_1020:
	v_mov_b64_e32 v[2:3], 0x200
	s_ashr_i32 s9, s8, 31
	v_cmp_lt_i64_e32 vcc, s[10:11], v[2:3]
	s_lshl_b64 s[10:11], s[8:9], 20
	s_add_u32 s10, s27, s10
	s_addc_u32 s11, s28, s11
	s_and_b64 s[12:13], vcc, exec
	s_cselect_b32 s9, s11, s21
	s_cselect_b32 s15, s10, s20
	s_ashr_i32 s3, s2, 31
	s_lshl_b64 s[12:13], s[2:3], 20
	s_add_u32 s12, s29, s12
	s_addc_u32 s13, s30, s13
	s_and_b64 s[22:23], vcc, exec
	s_cselect_b32 s3, s13, s19
	s_cselect_b32 s17, s12, s18
	s_add_u32 s46, s18, 0x100
	s_addc_u32 s47, s19, 0
	s_add_u32 s18, s20, 0x80080
	v_mov_b32_e32 v2, 0
	s_addc_u32 s19, s21, 0
	s_mov_b32 s48, -2
	v_mov_b32_e32 v3, v2
	v_mov_b32_e32 v4, v2
	v_mov_b32_e32 v5, v2
	v_mov_b32_e32 v6, v2
	v_mov_b32_e32 v7, v2
	v_mov_b32_e32 v8, v2
	v_mov_b32_e32 v9, v2
	v_mov_b32_e32 v18, v2
	v_mov_b32_e32 v19, v2
	v_mov_b32_e32 v20, v2
	v_mov_b32_e32 v21, v2
	v_mov_b32_e32 v22, v2
	v_mov_b32_e32 v23, v2
	v_mov_b32_e32 v24, v2
	v_mov_b32_e32 v25, v2
	v_mov_b32_e32 v34, v2
	v_mov_b32_e32 v35, v2
	v_mov_b32_e32 v36, v2
	v_mov_b32_e32 v37, v2
	v_mov_b32_e32 v38, v2
	v_mov_b32_e32 v39, v2
	v_mov_b32_e32 v40, v2
	v_mov_b32_e32 v41, v2
	v_mov_b32_e32 v50, v2
	v_mov_b32_e32 v51, v2
	v_mov_b32_e32 v52, v2
	v_mov_b32_e32 v53, v2
	v_mov_b32_e32 v54, v2
	v_mov_b32_e32 v55, v2
	v_mov_b32_e32 v56, v2
	v_mov_b32_e32 v57, v2
	v_mov_b32_e32 v10, v2
	v_mov_b32_e32 v11, v2
	v_mov_b32_e32 v12, v2
	v_mov_b32_e32 v13, v2
	v_mov_b32_e32 v14, v2
	v_mov_b32_e32 v15, v2
	v_mov_b32_e32 v16, v2
	v_mov_b32_e32 v17, v2
	v_mov_b32_e32 v26, v2
	v_mov_b32_e32 v27, v2
	v_mov_b32_e32 v28, v2
	v_mov_b32_e32 v29, v2
	v_mov_b32_e32 v30, v2
	v_mov_b32_e32 v31, v2
	v_mov_b32_e32 v32, v2
	v_mov_b32_e32 v33, v2
	v_mov_b32_e32 v42, v2
	v_mov_b32_e32 v43, v2
	v_mov_b32_e32 v44, v2
	v_mov_b32_e32 v45, v2
	v_mov_b32_e32 v46, v2
	v_mov_b32_e32 v47, v2
	v_mov_b32_e32 v48, v2
	v_mov_b32_e32 v49, v2
	v_mov_b32_e32 v58, v2
	v_mov_b32_e32 v59, v2
	v_mov_b32_e32 v60, v2
	v_mov_b32_e32 v61, v2
	v_mov_b32_e32 v62, v2
	v_mov_b32_e32 v63, v2
	v_mov_b32_e32 v64, v2
	v_mov_b32_e32 v65, v2
	v_mov_b32_e32 v66, v2
	v_mov_b32_e32 v67, v2
	v_mov_b32_e32 v68, v2
	v_mov_b32_e32 v69, v2
	v_mov_b32_e32 v70, v2
	v_mov_b32_e32 v71, v2
	v_mov_b32_e32 v72, v2
	v_mov_b32_e32 v73, v2
	s_waitcnt vmcnt(0)
	v_mov_b32_e32 v82, v2
	v_mov_b32_e32 v83, v2
	v_mov_b32_e32 v84, v2
	v_mov_b32_e32 v85, v2
	v_mov_b32_e32 v86, v2
	v_mov_b32_e32 v87, v2
	v_mov_b32_e32 v88, v2
	v_mov_b32_e32 v89, v2
	v_mov_b32_e32 v98, v2
	v_mov_b32_e32 v99, v2
	v_mov_b32_e32 v100, v2
	v_mov_b32_e32 v101, v2
	v_mov_b32_e32 v102, v2
	v_mov_b32_e32 v103, v2
	v_mov_b32_e32 v104, v2
	v_mov_b32_e32 v105, v2
	v_mov_b32_e32 v114, v2
	v_mov_b32_e32 v115, v2
	v_mov_b32_e32 v116, v2
	v_mov_b32_e32 v117, v2
	v_mov_b32_e32 v118, v2
	v_mov_b32_e32 v119, v2
	v_mov_b32_e32 v120, v2
	v_mov_b32_e32 v121, v2
	v_mov_b32_e32 v74, v2
	v_mov_b32_e32 v75, v2
	v_mov_b32_e32 v76, v2
	v_mov_b32_e32 v77, v2
	v_mov_b32_e32 v78, v2
	v_mov_b32_e32 v79, v2
	v_mov_b32_e32 v80, v2
	v_mov_b32_e32 v81, v2
	v_mov_b32_e32 v90, v2
	v_mov_b32_e32 v91, v2
	v_mov_b32_e32 v92, v2
	v_mov_b32_e32 v93, v2
	v_mov_b32_e32 v94, v2
	v_mov_b32_e32 v95, v2
	v_mov_b32_e32 v96, v2
	v_mov_b32_e32 v97, v2
	v_mov_b32_e32 v106, v2
	v_mov_b32_e32 v107, v2
	v_mov_b32_e32 v108, v2
	v_mov_b32_e32 v109, v2
	v_mov_b32_e32 v110, v2
	v_mov_b32_e32 v111, v2
	v_mov_b32_e32 v112, v2
	v_mov_b32_e32 v113, v2
	v_mov_b32_e32 v122, v2
	v_mov_b32_e32 v123, v2
	v_mov_b32_e32 v124, v2
	v_mov_b32_e32 v125, v2
	v_mov_b32_e32 v126, v2
	v_mov_b32_e32 v127, v2
	v_mov_b32_e32 v128, v2
	v_mov_b32_e32 v129, v2
	s_add_u32 s20, s18, 0xfff80080
	s_addc_u32 s21, s19, -1
	s_add_i32 s49, 0, 0x10000
	s_cmp_eq_u32 s48, 28
	s_cselect_b32 s23, s9, s21
	s_cselect_b32 s22, s15, s20
	s_cselect_b32 s21, s3, s47
	s_cselect_b32 s20, s17, s46
	s_add_i32 s52, 0, 0x14000
	v_add_u32_e32 v142, s49, v229
	v_add_u32_e32 v158, s52, v229
	ds_read_b128 v[130:133], v142
	ds_read_b128 v[134:137], v142 offset:1024
	ds_read_b128 v[138:141], v142 offset:2048
	ds_read_b128 v[142:145], v142 offset:3072
	ds_read_b128 v[146:149], v158
	ds_read_b128 v[150:153], v158 offset:1024
	ds_read_b128 v[154:157], v158 offset:2048
	ds_read_b128 v[158:161], v158 offset:3072
	s_add_i32 m0, s34, 0xc000
	ds_read_b128 v[162:165], v230
	ds_read_b128 v[166:169], v230 offset:1024
	ds_read_b128 v[170:173], v230 offset:2048
	ds_read_b128 v[174:177], v230 offset:3072
	ds_read_b128 v[178:181], v230 offset:4096
	ds_read_b128 v[182:185], v230 offset:5120
	ds_read_b128 v[186:189], v230 offset:6144
	ds_read_b128 v[190:193], v230 offset:7168
	global_load_lds_dwordx4 v208, s[18:19]
	s_add_i32 m0, s34, 0xe000
	s_nop 0
	global_load_lds_dwordx4 v206, s[18:19]
	s_waitcnt vmcnt(32)
	s_waitcnt lgkmcnt(0)
	s_barrier
; #define PG8_STAGE(bufoff, gbase, voff) do { _Pragma("unroll") for (int _i = 0; _i < 2; ++_i) \
;         __builtin_amdgcn_global_load_lds((const unsigned*)((const char*)(gbase) + (voff)[_i]), (LAS unsigned*)(lds + (bufoff) + ldsw + _i * 8192), 16, 0, 0); } while (0)
; #define PG8_LDA(dst, b, h) do { _Pragma("unroll") for (int m = 0; m < 4; ++m) _Pragma("unroll") for (int k = 0; k < 2; ++k) dst[m][k] = *(const LAS bf16x8*)(lds + PG8_SA(b, h) + aoff + m * 2048 + k * 1024); } while (0)
; #define PG8_MMA(ai, bj, At, Bt) do { __builtin_amdgcn_s_setprio(1); _Pragma("unroll") for (int m = 0; m < 4; ++m) _Pragma("unroll") for (int n = 0; n < 2; ++n) _Pragma("unroll") for (int k = 0; k < 2; ++k) \
;         acc[ai][bj][m][n] = __builtin_amdgcn_mfma_f32_16x16x32_bf16(Bt[n][k], At[m][k], acc[ai][bj][m][n], 0, 0, 0); __builtin_amdgcn_s_setprio(0); } while (0)
; #define PG8_WAIT_V(n) asm volatile("s_waitcnt vmcnt(" #n ")" ::: "memory")
; #define PG8_WAIT_L(n) asm volatile("s_waitcnt lgkmcnt(" #n ")" ::: "memory")
; #define PG8_BAR __builtin_amdgcn_s_barrier()
; #define PG8_SCHED __builtin_amdgcn_sched_barrier(0)
; template <class Epi, class Sched, int KC, bool ALIGN_EPI = false, bool SP2 = false, bool ATILED = false>
; __device__ __forceinline__ void gemm_phase(LAS unsigned char* lds, const Gemm g, const Sched& S, const Epi& E, int wave_s) {
;     ...
;             PG8_WAIT_V(8); PG8_WAIT_L(0); PG8_BAR; PG8_MMA(0, 0, At, B0); PG8_MMA(0, 1, At, B1); PG8_BAR; PG8_SCHED;
;             PG8_LDA(At, 0, 1); PG8_STAGE(PG8_SB(0, 0), b2, voffB); PG8_STAGE(PG8_SB(0, 1), b2 + hstepB, voffB); PG8_STAGE(PG8_SA(0, 0), a2, voffA);
;             PG8_WAIT_V(8); PG8_WAIT_L(0); PG8_BAR; PG8_MMA(1, 0, At, B0); PG8_MMA(1, 1, At, B1); PG8_BAR; PG8_SCHED;
	s_waitcnt lgkmcnt(0)
	v_mfma_f32_16x16x32_bf16 v[126:129], v[130:133], v[162:165], v[126:129]
	v_mfma_f32_16x16x32_bf16 v[122:125], v[138:141], v[162:165], v[122:125]
	v_mfma_f32_16x16x32_bf16 v[110:113], v[130:133], v[170:173], v[110:113]
	v_mfma_f32_16x16x32_bf16 v[106:109], v[138:141], v[170:173], v[106:109]
	v_mfma_f32_16x16x32_bf16 v[94:97], v[130:133], v[178:181], v[94:97]
	v_mfma_f32_16x16x32_bf16 v[90:93], v[138:141], v[178:181], v[90:93]
	v_mfma_f32_16x16x32_bf16 v[78:81], v[130:133], v[186:189], v[78:81]
	v_mfma_f32_16x16x32_bf16 v[74:77], v[138:141], v[186:189], v[74:77]
	v_mfma_f32_16x16x32_bf16 v[126:129], v[134:137], v[166:169], v[126:129]
	v_mfma_f32_16x16x32_bf16 v[122:125], v[142:145], v[166:169], v[122:125]
	v_mfma_f32_16x16x32_bf16 v[110:113], v[134:137], v[174:177], v[110:113]
	v_mfma_f32_16x16x32_bf16 v[106:109], v[142:145], v[174:177], v[106:109]
	v_mfma_f32_16x16x32_bf16 v[94:97], v[134:137], v[182:185], v[94:97]
	v_mfma_f32_16x16x32_bf16 v[90:93], v[142:145], v[182:185], v[90:93]
	v_mfma_f32_16x16x32_bf16 v[78:81], v[134:137], v[190:193], v[78:81]
	v_mfma_f32_16x16x32_bf16 v[74:77], v[142:145], v[190:193], v[74:77]
	v_mfma_f32_16x16x32_bf16 v[118:121], v[146:149], v[162:165], v[118:121]
	v_mfma_f32_16x16x32_bf16 v[114:117], v[154:157], v[162:165], v[114:117]
	v_mfma_f32_16x16x32_bf16 v[102:105], v[146:149], v[170:173], v[102:105]
	v_mfma_f32_16x16x32_bf16 v[98:101], v[154:157], v[170:173], v[98:101]
	v_mfma_f32_16x16x32_bf16 v[86:89], v[146:149], v[178:181], v[86:89]
	v_mfma_f32_16x16x32_bf16 v[82:85], v[154:157], v[178:181], v[82:85]
	v_mfma_f32_16x16x32_bf16 v[70:73], v[146:149], v[186:189], v[70:73]
	v_mfma_f32_16x16x32_bf16 v[66:69], v[154:157], v[186:189], v[66:69]
	v_mfma_f32_16x16x32_bf16 v[118:121], v[150:153], v[166:169], v[118:121]
	v_mfma_f32_16x16x32_bf16 v[114:117], v[158:161], v[166:169], v[114:117]
	v_mfma_f32_16x16x32_bf16 v[102:105], v[150:153], v[174:177], v[102:105]
	v_mfma_f32_16x16x32_bf16 v[98:101], v[158:161], v[174:177], v[98:101]
	v_mfma_f32_16x16x32_bf16 v[86:89], v[150:153], v[182:185], v[86:89]
	v_mfma_f32_16x16x32_bf16 v[82:85], v[158:161], v[182:185], v[82:85]
	v_mfma_f32_16x16x32_bf16 v[70:73], v[150:153], v[190:193], v[70:73]
	v_mfma_f32_16x16x32_bf16 v[66:69], v[158:161], v[190:193], v[66:69]
	s_barrier
	s_add_u32 s100, s22, 0x80
	s_addc_u32 s101, s23, 0
	s_add_i32 s49, s49, s31
	s_mov_b32 m0, s49
	ds_read_b128 v[162:165], v230 offset:16384
	ds_read_b128 v[166:169], v230 offset:17408
	ds_read_b128 v[170:173], v230 offset:18432
	ds_read_b128 v[174:177], v230 offset:19456
	ds_read_b128 v[178:181], v230 offset:20480
	ds_read_b128 v[182:185], v230 offset:21504
	ds_read_b128 v[186:189], v230 offset:22528
	ds_read_b128 v[190:193], v230 offset:23552
	global_load_lds_dwordx4 v0, s[20:21]
	s_add_i32 m0, s49, 0x2000
	s_add_u32 s50, s20, 0x20000
	s_addc_u32 s51, s21, 0
	s_add_i32 s49, s52, s31
	global_load_lds_dwordx4 v202, s[20:21]
	s_mov_b32 m0, s49
	s_nop 0
	global_load_lds_dwordx4 v0, s[50:51]
	s_add_i32 m0, s49, 0x2000
	s_nop 0
	global_load_lds_dwordx4 v202, s[50:51]
	s_mov_b32 m0, s34
	s_nop 0
	global_load_lds_dwordx4 v198, s[22:23]
	s_mov_b32 m0, s35
	s_nop 0
	global_load_lds_dwordx4 v200, s[22:23]
	s_waitcnt vmcnt(32)
	s_waitcnt lgkmcnt(0)
	s_barrier
	s_waitcnt lgkmcnt(0)
	v_mfma_f32_16x16x32_bf16 v[62:65], v[130:133], v[162:165], v[62:65]
	v_mfma_f32_16x16x32_bf16 v[58:61], v[138:141], v[162:165], v[58:61]
	v_mfma_f32_16x16x32_bf16 v[46:49], v[130:133], v[170:173], v[46:49]
	v_mfma_f32_16x16x32_bf16 v[42:45], v[138:141], v[170:173], v[42:45]
	v_mfma_f32_16x16x32_bf16 v[30:33], v[130:133], v[178:181], v[30:33]
	v_mfma_f32_16x16x32_bf16 v[26:29], v[138:141], v[178:181], v[26:29]
	v_mfma_f32_16x16x32_bf16 v[14:17], v[130:133], v[186:189], v[14:17]
	v_mfma_f32_16x16x32_bf16 v[10:13], v[138:141], v[186:189], v[10:13]
	v_mfma_f32_16x16x32_bf16 v[62:65], v[134:137], v[166:169], v[62:65]
	v_mfma_f32_16x16x32_bf16 v[58:61], v[142:145], v[166:169], v[58:61]
	v_mfma_f32_16x16x32_bf16 v[46:49], v[134:137], v[174:177], v[46:49]
	v_mfma_f32_16x16x32_bf16 v[42:45], v[142:145], v[174:177], v[42:45]
	v_mfma_f32_16x16x32_bf16 v[30:33], v[134:137], v[182:185], v[30:33]
	v_mfma_f32_16x16x32_bf16 v[26:29], v[142:145], v[182:185], v[26:29]
	v_mfma_f32_16x16x32_bf16 v[14:17], v[134:137], v[190:193], v[14:17]
	v_mfma_f32_16x16x32_bf16 v[10:13], v[142:145], v[190:193], v[10:13]
	v_mfma_f32_16x16x32_bf16 v[54:57], v[146:149], v[162:165], v[54:57]
	v_mfma_f32_16x16x32_bf16 v[50:53], v[154:157], v[162:165], v[50:53]
	v_mfma_f32_16x16x32_bf16 v[38:41], v[146:149], v[170:173], v[38:41]
	v_mfma_f32_16x16x32_bf16 v[34:37], v[154:157], v[170:173], v[34:37]
	v_mfma_f32_16x16x32_bf16 v[22:25], v[146:149], v[178:181], v[22:25]
	v_mfma_f32_16x16x32_bf16 v[18:21], v[154:157], v[178:181], v[18:21]
	v_mfma_f32_16x16x32_bf16 v[6:9], v[146:149], v[186:189], v[6:9]
	v_mfma_f32_16x16x32_bf16 v[2:5], v[154:157], v[186:189], v[2:5]
	v_mfma_f32_16x16x32_bf16 v[54:57], v[150:153], v[166:169], v[54:57]
	v_mfma_f32_16x16x32_bf16 v[50:53], v[158:161], v[166:169], v[50:53]
	v_mfma_f32_16x16x32_bf16 v[38:41], v[150:153], v[174:177], v[38:41]
	v_mfma_f32_16x16x32_bf16 v[34:37], v[158:161], v[174:177], v[34:37]
	v_mfma_f32_16x16x32_bf16 v[22:25], v[150:153], v[182:185], v[22:25]
	v_mfma_f32_16x16x32_bf16 v[18:21], v[158:161], v[182:185], v[18:21]
	v_mfma_f32_16x16x32_bf16 v[6:9], v[150:153], v[190:193], v[6:9]
	v_mfma_f32_16x16x32_bf16 v[2:5], v[158:161], v[190:193], v[2:5]
	s_barrier
; #define PG8_STAGE(bufoff, gbase, voff) do { _Pragma("unroll") for (int _i = 0; _i < 2; ++_i) \
;         __builtin_amdgcn_global_load_lds((const unsigned*)((const char*)(gbase) + (voff)[_i]), (LAS unsigned*)(lds + (bufoff) + ldsw + _i * 8192), 16, 0, 0); } while (0)
; #define PG8_LDA(dst, b, h) do { _Pragma("unroll") for (int m = 0; m < 4; ++m) _Pragma("unroll") for (int k = 0; k < 2; ++k) dst[m][k] = *(const LAS bf16x8*)(lds + PG8_SA(b, h) + aoff + m * 2048 + k * 1024); } while (0)
; #define PG8_LDB(dst, b, h) do { _Pragma("unroll") for (int n = 0; n < 2; ++n) _Pragma("unroll") for (int k = 0; k < 2; ++k) dst[n][k] = *(const LAS bf16x8*)(lds + PG8_SB(b, h) + boff + n * 2048 + k * 1024); } while (0)
; #define PG8_MMA(ai, bj, At, Bt) do { __builtin_amdgcn_s_setprio(1); _Pragma("unroll") for (int m = 0; m < 4; ++m) _Pragma("unroll") for (int n = 0; n < 2; ++n) _Pragma("unroll") for (int k = 0; k < 2; ++k) \
;         acc[ai][bj][m][n] = __builtin_amdgcn_mfma_f32_16x16x32_bf16(Bt[n][k], At[m][k], acc[ai][bj][m][n], 0, 0, 0); __builtin_amdgcn_s_setprio(0); } while (0)
; #define PG8_WAIT_V(n) asm volatile("s_waitcnt vmcnt(" #n ")" ::: "memory")
; #define PG8_WAIT_L(n) asm volatile("s_waitcnt lgkmcnt(" #n ")" ::: "memory")
; #define PG8_BAR __builtin_amdgcn_s_barrier()
; #define PG8_SCHED __builtin_amdgcn_sched_barrier(0)
; template <class Epi, class Sched, int KC, bool ALIGN_EPI = false, bool SP2 = false, bool ATILED = false>
; __device__ __forceinline__ void gemm_phase(LAS unsigned char* lds, const Gemm g, const Sched& S, const Epi& E, int wave_s) {
;     ...
;             PG8_LDB(B0, 1, 0); PG8_LDB(B1, 1, 1); PG8_SCHED; PG8_LDA(At, 1, 0); PG8_STAGE(PG8_SA(0, 1), a2 + hstepA, voffA);
;             PG8_WAIT_V(8); PG8_WAIT_L(0); PG8_BAR; PG8_MMA(0, 0, At, B0); PG8_MMA(0, 1, At, B1); PG8_BAR; PG8_SCHED;
;             PG8_LDA(At, 1, 1); PG8_STAGE(PG8_SB(1, 0), b3, voffB); PG8_STAGE(PG8_SB(1, 1), b3 + hstepB, voffB); PG8_STAGE(PG8_SA(1, 0), a3, voffA);
;             PG8_WAIT_V(8); PG8_WAIT_L(0); PG8_BAR; PG8_MMA(1, 0, At, B0); PG8_MMA(1, 1, At, B1); PG8_BAR; PG8_SCHED;
	s_add_i32 s49, 0, 0x18000
	s_add_i32 s50, 0, 0x1c000
	v_add_u32_e32 v142, s49, v229
	v_add_u32_e32 v158, s50, v229
	ds_read_b128 v[130:133], v142
	ds_read_b128 v[134:137], v142 offset:1024
	ds_read_b128 v[138:141], v142 offset:2048
	ds_read_b128 v[142:145], v142 offset:3072
	ds_read_b128 v[146:149], v158
	ds_read_b128 v[150:153], v158 offset:1024
	ds_read_b128 v[154:157], v158 offset:2048
	ds_read_b128 v[158:161], v158 offset:3072
	s_add_u32 s22, s22, 0x80000
	s_addc_u32 s23, s23, 0
	s_mov_b32 m0, s36
	ds_read_b128 v[162:165], v230 offset:32768
	ds_read_b128 v[166:169], v230 offset:33792
	ds_read_b128 v[170:173], v230 offset:34816
	ds_read_b128 v[174:177], v230 offset:35840
	ds_read_b128 v[178:181], v230 offset:36864
	ds_read_b128 v[182:185], v230 offset:37888
	ds_read_b128 v[186:189], v230 offset:38912
	ds_read_b128 v[190:193], v230 offset:39936
	global_load_lds_dwordx4 v198, s[22:23]
	s_mov_b32 m0, s37
	s_nop 0
	global_load_lds_dwordx4 v200, s[22:23]
	s_waitcnt vmcnt(8)
	s_waitcnt lgkmcnt(0)
	s_barrier
	s_waitcnt lgkmcnt(0)
	v_mfma_f32_16x16x32_bf16 v[126:129], v[130:133], v[162:165], v[126:129]
	v_mfma_f32_16x16x32_bf16 v[122:125], v[138:141], v[162:165], v[122:125]
	v_mfma_f32_16x16x32_bf16 v[110:113], v[130:133], v[170:173], v[110:113]
	v_mfma_f32_16x16x32_bf16 v[106:109], v[138:141], v[170:173], v[106:109]
	v_mfma_f32_16x16x32_bf16 v[94:97], v[130:133], v[178:181], v[94:97]
	v_mfma_f32_16x16x32_bf16 v[90:93], v[138:141], v[178:181], v[90:93]
	v_mfma_f32_16x16x32_bf16 v[78:81], v[130:133], v[186:189], v[78:81]
	v_mfma_f32_16x16x32_bf16 v[74:77], v[138:141], v[186:189], v[74:77]
	v_mfma_f32_16x16x32_bf16 v[126:129], v[134:137], v[166:169], v[126:129]
	v_mfma_f32_16x16x32_bf16 v[122:125], v[142:145], v[166:169], v[122:125]
	v_mfma_f32_16x16x32_bf16 v[110:113], v[134:137], v[174:177], v[110:113]
	v_mfma_f32_16x16x32_bf16 v[106:109], v[142:145], v[174:177], v[106:109]
	v_mfma_f32_16x16x32_bf16 v[94:97], v[134:137], v[182:185], v[94:97]
	v_mfma_f32_16x16x32_bf16 v[90:93], v[142:145], v[182:185], v[90:93]
	v_mfma_f32_16x16x32_bf16 v[78:81], v[134:137], v[190:193], v[78:81]
	v_mfma_f32_16x16x32_bf16 v[74:77], v[142:145], v[190:193], v[74:77]
	v_mfma_f32_16x16x32_bf16 v[118:121], v[146:149], v[162:165], v[118:121]
	v_mfma_f32_16x16x32_bf16 v[114:117], v[154:157], v[162:165], v[114:117]
	v_mfma_f32_16x16x32_bf16 v[102:105], v[146:149], v[170:173], v[102:105]
	v_mfma_f32_16x16x32_bf16 v[98:101], v[154:157], v[170:173], v[98:101]
	v_mfma_f32_16x16x32_bf16 v[86:89], v[146:149], v[178:181], v[86:89]
	v_mfma_f32_16x16x32_bf16 v[82:85], v[154:157], v[178:181], v[82:85]
	v_mfma_f32_16x16x32_bf16 v[70:73], v[146:149], v[186:189], v[70:73]
	v_mfma_f32_16x16x32_bf16 v[66:69], v[154:157], v[186:189], v[66:69]
	v_mfma_f32_16x16x32_bf16 v[118:121], v[150:153], v[166:169], v[118:121]
	v_mfma_f32_16x16x32_bf16 v[114:117], v[158:161], v[166:169], v[114:117]
	v_mfma_f32_16x16x32_bf16 v[102:105], v[150:153], v[174:177], v[102:105]
	v_mfma_f32_16x16x32_bf16 v[98:101], v[158:161], v[174:177], v[98:101]
	v_mfma_f32_16x16x32_bf16 v[86:89], v[150:153], v[182:185], v[86:89]
	v_mfma_f32_16x16x32_bf16 v[82:85], v[158:161], v[182:185], v[82:85]
	v_mfma_f32_16x16x32_bf16 v[70:73], v[150:153], v[190:193], v[70:73]
	v_mfma_f32_16x16x32_bf16 v[66:69], v[158:161], v[190:193], v[66:69]
	s_barrier
	s_add_u32 s98, s20, 0x80
	s_addc_u32 s99, s21, 0
	s_add_i32 s22, s49, s31
	s_mov_b32 m0, s22
	ds_read_b128 v[162:165], v230 offset:49152
	ds_read_b128 v[166:169], v230 offset:50176
	ds_read_b128 v[170:173], v230 offset:51200
	ds_read_b128 v[174:177], v230 offset:52224
	ds_read_b128 v[178:181], v230 offset:53248
	ds_read_b128 v[182:185], v230 offset:54272
	ds_read_b128 v[186:189], v230 offset:55296
	ds_read_b128 v[190:193], v230 offset:56320
	global_load_lds_dwordx4 v0, s[98:99]
	s_add_i32 m0, s22, 0x2000
	s_add_u32 s20, s20, 0x20080
	s_addc_u32 s21, s21, 0
	s_add_i32 s22, s50, s31
	global_load_lds_dwordx4 v202, s[98:99]
	s_mov_b32 m0, s22
	s_nop 0
	global_load_lds_dwordx4 v0, s[20:21]
	s_add_i32 m0, s22, 0x2000
	s_nop 0
	global_load_lds_dwordx4 v202, s[20:21]
	s_mov_b32 m0, s41
	s_nop 0
	global_load_lds_dwordx4 v198, s[100:101]
	s_mov_b32 m0, s42
	s_nop 0
	global_load_lds_dwordx4 v200, s[100:101]
	s_waitcnt vmcnt(8)
	s_waitcnt lgkmcnt(0)
	s_barrier
	s_waitcnt lgkmcnt(0)
	v_mfma_f32_16x16x32_bf16 v[62:65], v[130:133], v[162:165], v[62:65]
	v_mfma_f32_16x16x32_bf16 v[58:61], v[138:141], v[162:165], v[58:61]
	v_mfma_f32_16x16x32_bf16 v[46:49], v[130:133], v[170:173], v[46:49]
	v_mfma_f32_16x16x32_bf16 v[42:45], v[138:141], v[170:173], v[42:45]
	v_mfma_f32_16x16x32_bf16 v[30:33], v[130:133], v[178:181], v[30:33]
	v_mfma_f32_16x16x32_bf16 v[26:29], v[138:141], v[178:181], v[26:29]
	v_mfma_f32_16x16x32_bf16 v[14:17], v[130:133], v[186:189], v[14:17]
	v_mfma_f32_16x16x32_bf16 v[10:13], v[138:141], v[186:189], v[10:13]
	v_mfma_f32_16x16x32_bf16 v[62:65], v[134:137], v[166:169], v[62:65]
	v_mfma_f32_16x16x32_bf16 v[58:61], v[142:145], v[166:169], v[58:61]
	v_mfma_f32_16x16x32_bf16 v[46:49], v[134:137], v[174:177], v[46:49]
	v_mfma_f32_16x16x32_bf16 v[42:45], v[142:145], v[174:177], v[42:45]
	v_mfma_f32_16x16x32_bf16 v[30:33], v[134:137], v[182:185], v[30:33]
	v_mfma_f32_16x16x32_bf16 v[26:29], v[142:145], v[182:185], v[26:29]
	v_mfma_f32_16x16x32_bf16 v[14:17], v[134:137], v[190:193], v[14:17]
	v_mfma_f32_16x16x32_bf16 v[10:13], v[142:145], v[190:193], v[10:13]
	v_mfma_f32_16x16x32_bf16 v[54:57], v[146:149], v[162:165], v[54:57]
	v_mfma_f32_16x16x32_bf16 v[50:53], v[154:157], v[162:165], v[50:53]
	v_mfma_f32_16x16x32_bf16 v[38:41], v[146:149], v[170:173], v[38:41]
	v_mfma_f32_16x16x32_bf16 v[34:37], v[154:157], v[170:173], v[34:37]
	v_mfma_f32_16x16x32_bf16 v[22:25], v[146:149], v[178:181], v[22:25]
	v_mfma_f32_16x16x32_bf16 v[18:21], v[154:157], v[178:181], v[18:21]
	v_mfma_f32_16x16x32_bf16 v[6:9], v[146:149], v[186:189], v[6:9]
	v_mfma_f32_16x16x32_bf16 v[2:5], v[154:157], v[186:189], v[2:5]
	v_mfma_f32_16x16x32_bf16 v[54:57], v[150:153], v[166:169], v[54:57]
	v_mfma_f32_16x16x32_bf16 v[50:53], v[158:161], v[166:169], v[50:53]
	v_mfma_f32_16x16x32_bf16 v[38:41], v[150:153], v[174:177], v[38:41]
	v_mfma_f32_16x16x32_bf16 v[34:37], v[158:161], v[174:177], v[34:37]
	v_mfma_f32_16x16x32_bf16 v[22:25], v[150:153], v[182:185], v[22:25]
	v_mfma_f32_16x16x32_bf16 v[18:21], v[158:161], v[182:185], v[18:21]
	v_mfma_f32_16x16x32_bf16 v[6:9], v[150:153], v[190:193], v[6:9]
	v_mfma_f32_16x16x32_bf16 v[2:5], v[158:161], v[190:193], v[2:5]
	s_barrier
	s_add_i32 s48, s48, 2
	s_add_u32 s46, s46, 0x100
	s_addc_u32 s47, s47, 0
	s_add_u32 s18, s18, 0x100
	s_addc_u32 s19, s19, 0
	s_cmp_gt_u32 s48, 29
